# GEMM K-loops: the 16 per-K-step prefetch loads spread 2 per MFMA group over slices 0-1 (instead of 4 per group in slice 0); group-0 vmcnt recounted
# speedup vs baseline: 1.1354x; 1.0190x over previous
; #define GLOAD(RA, RB, kt) { _Pragma("unroll") for (int i = 0; i < 8; ++i) { const int ia = (tail && i >= 4) ? i - 4 : i; \
;     RA[i] = *(const u32x4*)(abase + ((size_t)(32 * ia) * lda + (kt) * 64) * 2 + aoff); RB[i] = *(const u32x4*)(bbase + ((size_t)(32 * i) * K + (kt) * 64) * 2 + boff); } }
; #define LWRITE(RA, RB, buf) { char* as_ = lds + (buf) * 2 * G_TILE; char* bs_ = as_ + G_TILE; _Pragma("unroll") for (int i = 0; i < 8; ++i) { *(u32x4*)(as_ + (lrow + 32 * i) * GS_B + lch * 16) = RA[i]; *(u32x4*)(bs_ + (lrow + 32 * i) * GS_B + lch * 16) = RB[i]; } }
; template <int EPI>
; DEV void gemm_tile(CParams& p, int layer, const bf16_t* __restrict__ A, int lda, const bf16_t* __restrict__ Bt, int K, int m0, int n0, int nt, char* lds, const int swave) {
;     ...
;   const char* asr = lds + (wm * 128 + lr) * GS_B + hh * 16;
;   const char* bsr = lds + G_TILE + (wn * 128 + lr) * GS_B + hh * 16;
;   char* wsw = lds + lrow * GS_B + lch * 16;
;     ...
;   GLOAD(ra0, rb0, 0); GLOAD(ra1, rb1, 1); LWRITE(ra0, rb0, 0); __syncthreads();
; #pragma unroll 1
;   for (int kt = 0; kt < nk; kt += 2) {
;     if (kt + 2 < nk) GLOAD(ra0, rb0, kt + 2);
;     COMPUTE(0, ra1, rb1, 1, true);
;     __syncthreads();
.LBB0_101:
	s_cmp_eq_u32 s36, 0
	s_cbranch_scc0 .Lzi_i1
	ds_read_b128 v[188:191], v49
	ds_read_b128 v[192:195], v49 offset:4608
	ds_read_b128 v[196:199], v49 offset:9216
	ds_read_b128 v[200:203], v49 offset:13824
	ds_read_b128 v[184:187], v48
	ds_read_b128 v[204:207], v48 offset:4608
	s_waitcnt lgkmcnt(1)
	v_mfma_f32_32x32x16_bf16 a[192:207], v[184:187], v[188:191], 0
	v_mfma_f32_32x32x16_bf16 a[128:143], v[184:187], v[192:195], 0
	v_mfma_f32_32x32x16_bf16 a[64:79], v[184:187], v[196:199], 0
	v_mfma_f32_32x32x16_bf16 a[0:15], v[184:187], v[200:203], 0
	ds_read_b128 v[184:187], v48 offset:9216
	ds_read_b128 v[208:211], v49 offset:32
	ds_read_b128 v[212:215], v49 offset:4640
	v_lshl_add_u64 v[50:51], v[0:1], 0, s[34:35]
	global_load_dwordx4 v[52:55], v[50:51], off
	v_lshl_add_u64 v[50:51], v[2:3], 0, s[34:35]
	s_or_b32 s2, s34, 0x10000
	s_mov_b32 s3, s35
	global_load_dwordx4 v[56:59], v[50:51], off
	s_waitcnt lgkmcnt(3)
	v_mfma_f32_32x32x16_bf16 a[208:223], v[204:207], v[188:191], 0
	v_mfma_f32_32x32x16_bf16 a[144:159], v[204:207], v[192:195], 0
	v_mfma_f32_32x32x16_bf16 a[80:95], v[204:207], v[196:199], 0
	v_mfma_f32_32x32x16_bf16 a[16:31], v[204:207], v[200:203], 0
	ds_read_b128 v[204:207], v48 offset:13824
	ds_read_b128 v[216:219], v49 offset:9248
	ds_read_b128 v[220:223], v49 offset:13856
	v_lshl_add_u64 v[50:51], v[0:1], 0, s[2:3]
	global_load_dwordx4 v[60:63], v[50:51], off
	v_lshl_add_u64 v[50:51], v[2:3], 0, s[2:3]
	s_or_b32 s2, s34, 0x20000
	global_load_dwordx4 v[68:71], v[50:51], off
	s_waitcnt lgkmcnt(5)
	v_mfma_f32_32x32x16_bf16 a[224:239], v[184:187], v[188:191], 0
	v_mfma_f32_32x32x16_bf16 a[160:175], v[184:187], v[192:195], 0
	v_mfma_f32_32x32x16_bf16 a[96:111], v[184:187], v[196:199], 0
	v_mfma_f32_32x32x16_bf16 a[32:47], v[184:187], v[200:203], 0
	ds_read_b128 v[184:187], v48 offset:32
	v_lshl_add_u64 v[50:51], v[0:1], 0, s[2:3]
	global_load_dwordx4 v[72:75], v[50:51], off
	v_lshl_add_u64 v[50:51], v[2:3], 0, s[2:3]
	s_or_b32 s2, s34, 0x30000
	global_load_dwordx4 v[76:79], v[50:51], off
	s_waitcnt lgkmcnt(3)
	v_mfma_f32_32x32x16_bf16 a[240:255], v[204:207], v[188:191], 0
	v_mfma_f32_32x32x16_bf16 a[176:191], v[204:207], v[192:195], 0
	v_mfma_f32_32x32x16_bf16 a[112:127], v[204:207], v[196:199], 0
	v_mfma_f32_32x32x16_bf16 a[48:63], v[204:207], v[200:203], 0
	ds_read_b128 v[204:207], v48 offset:4640
	v_lshl_add_u64 v[50:51], v[0:1], 0, s[2:3]
	global_load_dwordx4 v[80:83], v[50:51], off
	v_lshl_add_u64 v[50:51], v[2:3], 0, s[2:3]
	s_or_b32 s2, s34, 0x40000
	global_load_dwordx4 v[84:87], v[50:51], off
	s_waitcnt vmcnt(23)
	ds_write_b128 v31, v[100:103]
	s_waitcnt vmcnt(22)
	ds_write_b128 v32, v[104:107]
	s_waitcnt vmcnt(21)
	ds_write_b128 v41, v[112:115]
	s_waitcnt vmcnt(20)
	ds_write_b128 v42, v[116:119]
	s_waitcnt lgkmcnt(5)
	v_mfma_f32_32x32x16_bf16 a[192:207], v[184:187], v[208:211], a[192:207]
	v_mfma_f32_32x32x16_bf16 a[128:143], v[184:187], v[212:215], a[128:143]
	v_mfma_f32_32x32x16_bf16 a[64:79], v[184:187], v[216:219], a[64:79]
	v_mfma_f32_32x32x16_bf16 a[0:15], v[184:187], v[220:223], a[0:15]
	ds_read_b128 v[184:187], v48 offset:9248
	ds_read_b128 v[188:191], v49 offset:64
	ds_read_b128 v[192:195], v49 offset:4672
	v_lshl_add_u64 v[50:51], v[0:1], 0, s[2:3]
	global_load_dwordx4 v[88:91], v[50:51], off
	v_lshl_add_u64 v[50:51], v[2:3], 0, s[2:3]
	s_or_b32 s2, s34, 0x50000
	global_load_dwordx4 v[92:95], v[50:51], off
	s_waitcnt lgkmcnt(7)
	v_mfma_f32_32x32x16_bf16 a[208:223], v[204:207], v[208:211], a[208:223]
	v_mfma_f32_32x32x16_bf16 a[144:159], v[204:207], v[212:215], a[144:159]
	v_mfma_f32_32x32x16_bf16 a[80:95], v[204:207], v[216:219], a[80:95]
	v_mfma_f32_32x32x16_bf16 a[16:31], v[204:207], v[220:223], a[16:31]
	ds_read_b128 v[204:207], v48 offset:13856
	ds_read_b128 v[196:199], v49 offset:9280
	ds_read_b128 v[200:203], v49 offset:13888
	v_lshl_add_u64 v[50:51], v[0:1], 0, s[2:3]
	global_load_dwordx4 v[96:99], v[50:51], off
	v_lshl_add_u64 v[50:51], v[2:3], 0, s[2:3]
	s_or_b32 s2, s34, 0x60000
	global_load_dwordx4 v[108:111], v[50:51], off
	s_waitcnt lgkmcnt(5)
	v_mfma_f32_32x32x16_bf16 a[224:239], v[184:187], v[208:211], a[224:239]
	v_mfma_f32_32x32x16_bf16 a[160:175], v[184:187], v[212:215], a[160:175]
	v_mfma_f32_32x32x16_bf16 a[96:111], v[184:187], v[216:219], a[96:111]
	v_mfma_f32_32x32x16_bf16 a[32:47], v[184:187], v[220:223], a[32:47]
	ds_read_b128 v[184:187], v48 offset:64
	v_lshl_add_u64 v[50:51], v[0:1], 0, s[2:3]
	global_load_dwordx4 v[124:127], v[50:51], off
	v_lshl_add_u64 v[50:51], v[2:3], 0, s[2:3]
	s_or_b32 s34, s34, 0x70000
	global_load_dwordx4 v[144:147], v[50:51], off
	s_waitcnt lgkmcnt(3)
	v_mfma_f32_32x32x16_bf16 a[240:255], v[204:207], v[208:211], a[240:255]
	v_mfma_f32_32x32x16_bf16 a[176:191], v[204:207], v[212:215], a[176:191]
	v_mfma_f32_32x32x16_bf16 a[112:127], v[204:207], v[216:219], a[112:127]
	v_mfma_f32_32x32x16_bf16 a[48:63], v[204:207], v[220:223], a[48:63]
	ds_read_b128 v[204:207], v48 offset:4672
	v_lshl_add_u64 v[50:51], v[0:1], 0, s[34:35]
	global_load_dwordx4 v[160:163], v[50:51], off
	v_lshl_add_u64 v[50:51], v[2:3], 0, s[34:35]
	global_load_dwordx4 v[180:183], v[50:51], off
	s_waitcnt vmcnt(27)
	ds_write_b128 v37, v[120:123]
	s_waitcnt vmcnt(26)
	ds_write_b128 v38, v[128:131]
	s_waitcnt vmcnt(25)
	ds_write_b128 v39, v[132:135]
	s_waitcnt vmcnt(24)
	ds_write_b128 v40, v[136:139]
	s_waitcnt lgkmcnt(5)
	v_mfma_f32_32x32x16_bf16 a[192:207], v[184:187], v[188:191], a[192:207]
	v_mfma_f32_32x32x16_bf16 a[128:143], v[184:187], v[192:195], a[128:143]
	v_mfma_f32_32x32x16_bf16 a[64:79], v[184:187], v[196:199], a[64:79]
	v_mfma_f32_32x32x16_bf16 a[0:15], v[184:187], v[200:203], a[0:15]
	ds_read_b128 v[184:187], v48 offset:9280
	ds_read_b128 v[208:211], v49 offset:96
	ds_read_b128 v[212:215], v49 offset:4704
	s_waitcnt lgkmcnt(7)
; #define GLOAD(RA, RB, kt) { _Pragma("unroll") for (int i = 0; i < 8; ++i) { const int ia = (tail && i >= 4) ? i - 4 : i; \
;     RA[i] = *(const u32x4*)(abase + ((size_t)(32 * ia) * lda + (kt) * 64) * 2 + aoff); RB[i] = *(const u32x4*)(bbase + ((size_t)(32 * i) * K + (kt) * 64) * 2 + boff); } }
; #define LWRITE(RA, RB, buf) { char* as_ = lds + (buf) * 2 * G_TILE; char* bs_ = as_ + G_TILE; _Pragma("unroll") for (int i = 0; i < 8; ++i) { *(u32x4*)(as_ + (lrow + 32 * i) * GS_B + lch * 16) = RA[i]; *(u32x4*)(bs_ + (lrow + 32 * i) * GS_B + lch * 16) = RB[i]; } }
; template <int EPI>
; DEV void gemm_tile(CParams& p, int layer, const bf16_t* __restrict__ A, int lda, const bf16_t* __restrict__ Bt, int K, int m0, int n0, int nt, char* lds, const int swave) {
;     ...
;   GLOAD(ra0, rb0, 0); GLOAD(ra1, rb1, 1); LWRITE(ra0, rb0, 0); __syncthreads();
; #pragma unroll 1
;   for (int kt = 0; kt < nk; kt += 2) {
;     if (kt + 2 < nk) GLOAD(ra0, rb0, kt + 2);
;     COMPUTE(0, ra1, rb1, 1, true);
;     __syncthreads();
	v_mfma_f32_32x32x16_bf16 a[208:223], v[204:207], v[188:191], a[208:223]
	v_mfma_f32_32x32x16_bf16 a[144:159], v[204:207], v[192:195], a[144:159]
	v_mfma_f32_32x32x16_bf16 a[80:95], v[204:207], v[196:199], a[80:95]
	v_mfma_f32_32x32x16_bf16 a[16:31], v[204:207], v[200:203], a[16:31]
	ds_read_b128 v[204:207], v48 offset:13888
	ds_read_b128 v[216:219], v49 offset:9312
	ds_read_b128 v[220:223], v49 offset:13920
	s_waitcnt lgkmcnt(5)
	v_mfma_f32_32x32x16_bf16 a[224:239], v[184:187], v[188:191], a[224:239]
	v_mfma_f32_32x32x16_bf16 a[160:175], v[184:187], v[192:195], a[160:175]
	v_mfma_f32_32x32x16_bf16 a[96:111], v[184:187], v[196:199], a[96:111]
	v_mfma_f32_32x32x16_bf16 a[32:47], v[184:187], v[200:203], a[32:47]
	ds_read_b128 v[184:187], v48 offset:96
	s_waitcnt lgkmcnt(3)
	v_mfma_f32_32x32x16_bf16 a[240:255], v[204:207], v[188:191], a[240:255]
	v_mfma_f32_32x32x16_bf16 a[176:191], v[204:207], v[192:195], a[176:191]
	v_mfma_f32_32x32x16_bf16 a[112:127], v[204:207], v[196:199], a[112:127]
	v_mfma_f32_32x32x16_bf16 a[48:63], v[204:207], v[200:203], a[48:63]
	ds_read_b128 v[204:207], v48 offset:4704
	s_waitcnt vmcnt(23)
	ds_write_b128 v33, v[140:143]
	s_waitcnt vmcnt(22)
	ds_write_b128 v34, v[148:151]
	s_waitcnt vmcnt(21)
	ds_write_b128 v35, v[152:155]
	s_waitcnt vmcnt(20)
	ds_write_b128 v36, v[156:159]
	s_waitcnt lgkmcnt(5)
	v_mfma_f32_32x32x16_bf16 a[192:207], v[184:187], v[208:211], a[192:207]
	v_mfma_f32_32x32x16_bf16 a[128:143], v[184:187], v[212:215], a[128:143]
	v_mfma_f32_32x32x16_bf16 a[64:79], v[184:187], v[216:219], a[64:79]
	v_mfma_f32_32x32x16_bf16 a[0:15], v[184:187], v[220:223], a[0:15]
	ds_read_b128 v[184:187], v48 offset:9312
	s_waitcnt lgkmcnt(5)
	v_mfma_f32_32x32x16_bf16 a[208:223], v[204:207], v[208:211], a[208:223]
	v_mfma_f32_32x32x16_bf16 a[144:159], v[204:207], v[212:215], a[144:159]
	v_mfma_f32_32x32x16_bf16 a[80:95], v[204:207], v[216:219], a[80:95]
	v_mfma_f32_32x32x16_bf16 a[16:31], v[204:207], v[220:223], a[16:31]
	ds_read_b128 v[204:207], v48 offset:13920
	s_waitcnt lgkmcnt(1)
	v_mfma_f32_32x32x16_bf16 a[224:239], v[184:187], v[208:211], a[224:239]
	v_mfma_f32_32x32x16_bf16 a[160:175], v[184:187], v[212:215], a[160:175]
	v_mfma_f32_32x32x16_bf16 a[96:111], v[184:187], v[216:219], a[96:111]
	v_mfma_f32_32x32x16_bf16 a[32:47], v[184:187], v[220:223], a[32:47]
	s_waitcnt lgkmcnt(0)
	v_mfma_f32_32x32x16_bf16 a[240:255], v[204:207], v[208:211], a[240:255]
	v_mfma_f32_32x32x16_bf16 a[176:191], v[204:207], v[212:215], a[176:191]
	v_mfma_f32_32x32x16_bf16 a[112:127], v[204:207], v[216:219], a[112:127]
	v_mfma_f32_32x32x16_bf16 a[48:63], v[204:207], v[220:223], a[48:63]
	s_waitcnt vmcnt(19)
	ds_write_b128 v43, v[164:167]
	s_waitcnt vmcnt(18)
	ds_write_b128 v44, v[168:171]
	s_waitcnt vmcnt(17)
	ds_write_b128 v45, v[172:175]
	s_waitcnt vmcnt(16)
	ds_write_b128 v46, v[176:179]
	s_branch .LBB0_117
.Lzi_i1:
	ds_read_b128 v[188:191], v49
	ds_read_b128 v[192:195], v49 offset:4608
	ds_read_b128 v[196:199], v49 offset:9216
	ds_read_b128 v[200:203], v49 offset:13824
	ds_read_b128 v[184:187], v48
	ds_read_b128 v[204:207], v48 offset:4608
	s_waitcnt lgkmcnt(1)
	v_mfma_f32_32x32x16_bf16 a[192:207], v[184:187], v[188:191], a[192:207]
	v_mfma_f32_32x32x16_bf16 a[128:143], v[184:187], v[192:195], a[128:143]
	v_mfma_f32_32x32x16_bf16 a[64:79], v[184:187], v[196:199], a[64:79]
	v_mfma_f32_32x32x16_bf16 a[0:15], v[184:187], v[200:203], a[0:15]
	ds_read_b128 v[184:187], v48 offset:9216
	ds_read_b128 v[208:211], v49 offset:32
	ds_read_b128 v[212:215], v49 offset:4640
	v_lshl_add_u64 v[50:51], v[0:1], 0, s[34:35]
	global_load_dwordx4 v[52:55], v[50:51], off
	v_lshl_add_u64 v[50:51], v[2:3], 0, s[34:35]
	s_or_b32 s2, s34, 0x10000
	s_mov_b32 s3, s35
	global_load_dwordx4 v[56:59], v[50:51], off
	s_waitcnt lgkmcnt(3)
	v_mfma_f32_32x32x16_bf16 a[208:223], v[204:207], v[188:191], a[208:223]
	v_mfma_f32_32x32x16_bf16 a[144:159], v[204:207], v[192:195], a[144:159]
	v_mfma_f32_32x32x16_bf16 a[80:95], v[204:207], v[196:199], a[80:95]
	v_mfma_f32_32x32x16_bf16 a[16:31], v[204:207], v[200:203], a[16:31]
	ds_read_b128 v[204:207], v48 offset:13824
	ds_read_b128 v[216:219], v49 offset:9248
	ds_read_b128 v[220:223], v49 offset:13856
	v_lshl_add_u64 v[50:51], v[0:1], 0, s[2:3]
	global_load_dwordx4 v[60:63], v[50:51], off
	v_lshl_add_u64 v[50:51], v[2:3], 0, s[2:3]
	s_or_b32 s2, s34, 0x20000
	global_load_dwordx4 v[68:71], v[50:51], off
	s_waitcnt lgkmcnt(5)
	v_mfma_f32_32x32x16_bf16 a[224:239], v[184:187], v[188:191], a[224:239]
	v_mfma_f32_32x32x16_bf16 a[160:175], v[184:187], v[192:195], a[160:175]
	v_mfma_f32_32x32x16_bf16 a[96:111], v[184:187], v[196:199], a[96:111]
	v_mfma_f32_32x32x16_bf16 a[32:47], v[184:187], v[200:203], a[32:47]
	ds_read_b128 v[184:187], v48 offset:32
	v_lshl_add_u64 v[50:51], v[0:1], 0, s[2:3]
	global_load_dwordx4 v[72:75], v[50:51], off
	v_lshl_add_u64 v[50:51], v[2:3], 0, s[2:3]
	s_or_b32 s2, s34, 0x30000
	global_load_dwordx4 v[76:79], v[50:51], off
	s_waitcnt lgkmcnt(3)
	v_mfma_f32_32x32x16_bf16 a[240:255], v[204:207], v[188:191], a[240:255]
	v_mfma_f32_32x32x16_bf16 a[176:191], v[204:207], v[192:195], a[176:191]
	v_mfma_f32_32x32x16_bf16 a[112:127], v[204:207], v[196:199], a[112:127]
	v_mfma_f32_32x32x16_bf16 a[48:63], v[204:207], v[200:203], a[48:63]
	ds_read_b128 v[204:207], v48 offset:4640
	v_lshl_add_u64 v[50:51], v[0:1], 0, s[2:3]
	global_load_dwordx4 v[80:83], v[50:51], off
	v_lshl_add_u64 v[50:51], v[2:3], 0, s[2:3]
	s_or_b32 s2, s34, 0x40000
	global_load_dwordx4 v[84:87], v[50:51], off
	s_waitcnt vmcnt(23)
	ds_write_b128 v31, v[100:103]
	s_waitcnt vmcnt(22)
	ds_write_b128 v32, v[104:107]
	s_waitcnt vmcnt(21)
; #define GLOAD(RA, RB, kt) { _Pragma("unroll") for (int i = 0; i < 8; ++i) { const int ia = (tail && i >= 4) ? i - 4 : i; \
;     RA[i] = *(const u32x4*)(abase + ((size_t)(32 * ia) * lda + (kt) * 64) * 2 + aoff); RB[i] = *(const u32x4*)(bbase + ((size_t)(32 * i) * K + (kt) * 64) * 2 + boff); } }
; #define LWRITE(RA, RB, buf) { char* as_ = lds + (buf) * 2 * G_TILE; char* bs_ = as_ + G_TILE; _Pragma("unroll") for (int i = 0; i < 8; ++i) { *(u32x4*)(as_ + (lrow + 32 * i) * GS_B + lch * 16) = RA[i]; *(u32x4*)(bs_ + (lrow + 32 * i) * GS_B + lch * 16) = RB[i]; } }
; template <int EPI>
; DEV void gemm_tile(CParams& p, int layer, const bf16_t* __restrict__ A, int lda, const bf16_t* __restrict__ Bt, int K, int m0, int n0, int nt, char* lds, const int swave) {
;     ...
;   GLOAD(ra0, rb0, 0); GLOAD(ra1, rb1, 1); LWRITE(ra0, rb0, 0); __syncthreads();
; #pragma unroll 1
;   for (int kt = 0; kt < nk; kt += 2) {
;     if (kt + 2 < nk) GLOAD(ra0, rb0, kt + 2);
;     COMPUTE(0, ra1, rb1, 1, true);
;     __syncthreads();
	ds_write_b128 v41, v[112:115]
	s_waitcnt vmcnt(20)
	ds_write_b128 v42, v[116:119]
	s_waitcnt lgkmcnt(5)
	v_mfma_f32_32x32x16_bf16 a[192:207], v[184:187], v[208:211], a[192:207]
	v_mfma_f32_32x32x16_bf16 a[128:143], v[184:187], v[212:215], a[128:143]
	v_mfma_f32_32x32x16_bf16 a[64:79], v[184:187], v[216:219], a[64:79]
	v_mfma_f32_32x32x16_bf16 a[0:15], v[184:187], v[220:223], a[0:15]
	ds_read_b128 v[184:187], v48 offset:9248
	ds_read_b128 v[188:191], v49 offset:64
	ds_read_b128 v[192:195], v49 offset:4672
	v_lshl_add_u64 v[50:51], v[0:1], 0, s[2:3]
	global_load_dwordx4 v[88:91], v[50:51], off
	v_lshl_add_u64 v[50:51], v[2:3], 0, s[2:3]
	s_or_b32 s2, s34, 0x50000
	global_load_dwordx4 v[92:95], v[50:51], off
	s_waitcnt lgkmcnt(7)
	v_mfma_f32_32x32x16_bf16 a[208:223], v[204:207], v[208:211], a[208:223]
	v_mfma_f32_32x32x16_bf16 a[144:159], v[204:207], v[212:215], a[144:159]
	v_mfma_f32_32x32x16_bf16 a[80:95], v[204:207], v[216:219], a[80:95]
	v_mfma_f32_32x32x16_bf16 a[16:31], v[204:207], v[220:223], a[16:31]
	ds_read_b128 v[204:207], v48 offset:13856
	ds_read_b128 v[196:199], v49 offset:9280
	ds_read_b128 v[200:203], v49 offset:13888
	v_lshl_add_u64 v[50:51], v[0:1], 0, s[2:3]
	global_load_dwordx4 v[96:99], v[50:51], off
	v_lshl_add_u64 v[50:51], v[2:3], 0, s[2:3]
	s_or_b32 s2, s34, 0x60000
	global_load_dwordx4 v[108:111], v[50:51], off
	s_waitcnt lgkmcnt(5)
	v_mfma_f32_32x32x16_bf16 a[224:239], v[184:187], v[208:211], a[224:239]
	v_mfma_f32_32x32x16_bf16 a[160:175], v[184:187], v[212:215], a[160:175]
	v_mfma_f32_32x32x16_bf16 a[96:111], v[184:187], v[216:219], a[96:111]
	v_mfma_f32_32x32x16_bf16 a[32:47], v[184:187], v[220:223], a[32:47]
	ds_read_b128 v[184:187], v48 offset:64
	v_lshl_add_u64 v[50:51], v[0:1], 0, s[2:3]
	global_load_dwordx4 v[124:127], v[50:51], off
	v_lshl_add_u64 v[50:51], v[2:3], 0, s[2:3]
	s_or_b32 s34, s34, 0x70000
	global_load_dwordx4 v[144:147], v[50:51], off
	s_waitcnt lgkmcnt(3)
	v_mfma_f32_32x32x16_bf16 a[240:255], v[204:207], v[208:211], a[240:255]
	v_mfma_f32_32x32x16_bf16 a[176:191], v[204:207], v[212:215], a[176:191]
	v_mfma_f32_32x32x16_bf16 a[112:127], v[204:207], v[216:219], a[112:127]
	v_mfma_f32_32x32x16_bf16 a[48:63], v[204:207], v[220:223], a[48:63]
	ds_read_b128 v[204:207], v48 offset:4672
	v_lshl_add_u64 v[50:51], v[0:1], 0, s[34:35]
	global_load_dwordx4 v[160:163], v[50:51], off
	v_lshl_add_u64 v[50:51], v[2:3], 0, s[34:35]
	global_load_dwordx4 v[180:183], v[50:51], off
	s_waitcnt vmcnt(27)
	ds_write_b128 v37, v[120:123]
	s_waitcnt vmcnt(26)
	ds_write_b128 v38, v[128:131]
	s_waitcnt vmcnt(25)
	ds_write_b128 v39, v[132:135]
	s_waitcnt vmcnt(24)
	ds_write_b128 v40, v[136:139]
	s_waitcnt lgkmcnt(5)
	v_mfma_f32_32x32x16_bf16 a[192:207], v[184:187], v[188:191], a[192:207]
	v_mfma_f32_32x32x16_bf16 a[128:143], v[184:187], v[192:195], a[128:143]
	v_mfma_f32_32x32x16_bf16 a[64:79], v[184:187], v[196:199], a[64:79]
	v_mfma_f32_32x32x16_bf16 a[0:15], v[184:187], v[200:203], a[0:15]
	ds_read_b128 v[184:187], v48 offset:9280
	ds_read_b128 v[208:211], v49 offset:96
	ds_read_b128 v[212:215], v49 offset:4704
	s_waitcnt lgkmcnt(7)
	v_mfma_f32_32x32x16_bf16 a[208:223], v[204:207], v[188:191], a[208:223]
	v_mfma_f32_32x32x16_bf16 a[144:159], v[204:207], v[192:195], a[144:159]
	v_mfma_f32_32x32x16_bf16 a[80:95], v[204:207], v[196:199], a[80:95]
	v_mfma_f32_32x32x16_bf16 a[16:31], v[204:207], v[200:203], a[16:31]
	ds_read_b128 v[204:207], v48 offset:13888
	ds_read_b128 v[216:219], v49 offset:9312
	ds_read_b128 v[220:223], v49 offset:13920
	s_waitcnt lgkmcnt(5)
	v_mfma_f32_32x32x16_bf16 a[224:239], v[184:187], v[188:191], a[224:239]
	v_mfma_f32_32x32x16_bf16 a[160:175], v[184:187], v[192:195], a[160:175]
	v_mfma_f32_32x32x16_bf16 a[96:111], v[184:187], v[196:199], a[96:111]
	v_mfma_f32_32x32x16_bf16 a[32:47], v[184:187], v[200:203], a[32:47]
	ds_read_b128 v[184:187], v48 offset:96
	s_waitcnt lgkmcnt(3)
	v_mfma_f32_32x32x16_bf16 a[240:255], v[204:207], v[188:191], a[240:255]
	v_mfma_f32_32x32x16_bf16 a[176:191], v[204:207], v[192:195], a[176:191]
	v_mfma_f32_32x32x16_bf16 a[112:127], v[204:207], v[196:199], a[112:127]
	v_mfma_f32_32x32x16_bf16 a[48:63], v[204:207], v[200:203], a[48:63]
	ds_read_b128 v[204:207], v48 offset:4704
	s_waitcnt vmcnt(23)
	ds_write_b128 v33, v[140:143]
	s_waitcnt vmcnt(22)
	ds_write_b128 v34, v[148:151]
	s_waitcnt vmcnt(21)
	ds_write_b128 v35, v[152:155]
	s_waitcnt vmcnt(20)
	ds_write_b128 v36, v[156:159]
	s_waitcnt lgkmcnt(5)
	v_mfma_f32_32x32x16_bf16 a[192:207], v[184:187], v[208:211], a[192:207]
	v_mfma_f32_32x32x16_bf16 a[128:143], v[184:187], v[212:215], a[128:143]
	v_mfma_f32_32x32x16_bf16 a[64:79], v[184:187], v[216:219], a[64:79]
	v_mfma_f32_32x32x16_bf16 a[0:15], v[184:187], v[220:223], a[0:15]
	ds_read_b128 v[184:187], v48 offset:9312
	s_waitcnt lgkmcnt(5)
	v_mfma_f32_32x32x16_bf16 a[208:223], v[204:207], v[208:211], a[208:223]
	v_mfma_f32_32x32x16_bf16 a[144:159], v[204:207], v[212:215], a[144:159]
	v_mfma_f32_32x32x16_bf16 a[80:95], v[204:207], v[216:219], a[80:95]
	v_mfma_f32_32x32x16_bf16 a[16:31], v[204:207], v[220:223], a[16:31]
	ds_read_b128 v[204:207], v48 offset:13920
	s_waitcnt lgkmcnt(1)
	v_mfma_f32_32x32x16_bf16 a[224:239], v[184:187], v[208:211], a[224:239]
	v_mfma_f32_32x32x16_bf16 a[160:175], v[184:187], v[212:215], a[160:175]
	v_mfma_f32_32x32x16_bf16 a[96:111], v[184:187], v[216:219], a[96:111]
	v_mfma_f32_32x32x16_bf16 a[32:47], v[184:187], v[220:223], a[32:47]
	s_waitcnt lgkmcnt(0)
	v_mfma_f32_32x32x16_bf16 a[240:255], v[204:207], v[208:211], a[240:255]
	v_mfma_f32_32x32x16_bf16 a[176:191], v[204:207], v[212:215], a[176:191]
	v_mfma_f32_32x32x16_bf16 a[112:127], v[204:207], v[216:219], a[112:127]
	v_mfma_f32_32x32x16_bf16 a[48:63], v[204:207], v[220:223], a[48:63]
	s_waitcnt vmcnt(19)
	ds_write_b128 v43, v[164:167]
	s_waitcnt vmcnt(18)
	ds_write_b128 v44, v[168:171]
	s_waitcnt vmcnt(17)
	ds_write_b128 v45, v[172:175]
	s_waitcnt vmcnt(16)
	ds_write_b128 v46, v[176:179]

; #define GLOAD(RA, RB, kt) { _Pragma("unroll") for (int i = 0; i < 8; ++i) { const int ia = (tail && i >= 4) ? i - 4 : i; \
;     RA[i] = *(const u32x4*)(abase + ((size_t)(32 * ia) * lda + (kt) * 64) * 2 + aoff); RB[i] = *(const u32x4*)(bbase + ((size_t)(32 * i) * K + (kt) * 64) * 2 + boff); } }
; template <int EPI>
; DEV void gemm_tile(CParams& p, int layer, const bf16_t* __restrict__ A, int lda, const bf16_t* __restrict__ Bt, int K, int m0, int n0, int nt, char* lds, const int swave) {
;     ...
;     const bool more = kt + 2 < nk;
;     if (kt + 3 < nk) GLOAD(ra1, rb1, kt + 3);
;     COMPUTE(1, ra0, rb0, 0, more);
;     __syncthreads();
.LBB0_119:
	v_add_u32_e32 v224, 0x1b000, v29
	v_add_u32_e32 v225, 0x12000, v49
	s_andn2_b64 vcc, exec, s[60:61]
	s_cbranch_vccnz .Lpg_i1_nomore
	ds_read_b128 v[188:191], v225
	ds_read_b128 v[192:195], v225 offset:4608
	ds_read_b128 v[196:199], v225 offset:9216
	ds_read_b128 v[200:203], v225 offset:13824
	ds_read_b128 v[184:187], v224
	ds_read_b128 v[204:207], v224 offset:4608
	s_waitcnt lgkmcnt(1)
	v_mfma_f32_32x32x16_bf16 a[192:207], v[184:187], v[188:191], a[192:207]
	v_mfma_f32_32x32x16_bf16 a[128:143], v[184:187], v[192:195], a[128:143]
	v_mfma_f32_32x32x16_bf16 a[64:79], v[184:187], v[196:199], a[64:79]
	v_mfma_f32_32x32x16_bf16 a[0:15], v[184:187], v[200:203], a[0:15]
	ds_read_b128 v[184:187], v224 offset:9216
	ds_read_b128 v[208:211], v225 offset:32
	ds_read_b128 v[212:215], v225 offset:4640
	s_lshl_b32 s34, s36, 7
	v_lshl_add_u64 v[50:51], v[0:1], 0, s[34:35]
	v_lshl_add_u64 v[64:65], v[2:3], 0, s[34:35]
	global_load_dwordx4 v[100:103], v[50:51], off offset:384
	global_load_dwordx4 v[104:107], v[64:65], off offset:384
	s_waitcnt lgkmcnt(3)
	v_mfma_f32_32x32x16_bf16 a[208:223], v[204:207], v[188:191], a[208:223]
	v_mfma_f32_32x32x16_bf16 a[144:159], v[204:207], v[192:195], a[144:159]
	v_mfma_f32_32x32x16_bf16 a[80:95], v[204:207], v[196:199], a[80:95]
	v_mfma_f32_32x32x16_bf16 a[16:31], v[204:207], v[200:203], a[16:31]
	ds_read_b128 v[204:207], v224 offset:13824
	ds_read_b128 v[216:219], v225 offset:9248
	ds_read_b128 v[220:223], v225 offset:13856
	v_add_co_u32_e32 v50, vcc, 0x10000, v50
	s_nop 1
	v_addc_co_u32_e32 v51, vcc, 0, v51, vcc
	v_add_co_u32_e32 v64, vcc, 0x10000, v64
	s_nop 1
	v_addc_co_u32_e32 v65, vcc, 0, v65, vcc
	global_load_dwordx4 v[112:115], v[50:51], off offset:384
	global_load_dwordx4 v[116:119], v[64:65], off offset:384
	s_waitcnt lgkmcnt(5)
	v_mfma_f32_32x32x16_bf16 a[224:239], v[184:187], v[188:191], a[224:239]
	v_mfma_f32_32x32x16_bf16 a[160:175], v[184:187], v[192:195], a[160:175]
	v_mfma_f32_32x32x16_bf16 a[96:111], v[184:187], v[196:199], a[96:111]
	v_mfma_f32_32x32x16_bf16 a[32:47], v[184:187], v[200:203], a[32:47]
	ds_read_b128 v[184:187], v224 offset:32
	v_lshl_add_u64 v[50:51], v[4:5], 0, s[34:35]
	v_lshl_add_u64 v[64:65], v[6:7], 0, s[34:35]
	global_load_dwordx4 v[120:123], v[50:51], off offset:384
	global_load_dwordx4 v[128:131], v[64:65], off offset:384
	s_waitcnt lgkmcnt(3)
	v_mfma_f32_32x32x16_bf16 a[240:255], v[204:207], v[188:191], a[240:255]
	v_mfma_f32_32x32x16_bf16 a[176:191], v[204:207], v[192:195], a[176:191]
	v_mfma_f32_32x32x16_bf16 a[112:127], v[204:207], v[196:199], a[112:127]
	v_mfma_f32_32x32x16_bf16 a[48:63], v[204:207], v[200:203], a[48:63]
	ds_read_b128 v[204:207], v224 offset:4640
	v_lshl_add_u64 v[50:51], v[8:9], 0, s[34:35]
	v_lshl_add_u64 v[64:65], v[10:11], 0, s[34:35]
	global_load_dwordx4 v[132:135], v[50:51], off offset:384
	global_load_dwordx4 v[136:139], v[64:65], off offset:384
	s_waitcnt vmcnt(23)
	ds_write_b128 v30, v[52:55]
	s_waitcnt vmcnt(22)
	ds_write_b128 v30, v[56:59] offset:36864
	s_waitcnt vmcnt(21)
	ds_write_b128 v30, v[60:63] offset:4608
	s_waitcnt vmcnt(20)
	ds_write_b128 v30, v[68:71] offset:41472
	s_waitcnt lgkmcnt(5)
	v_mfma_f32_32x32x16_bf16 a[192:207], v[184:187], v[208:211], a[192:207]
	v_mfma_f32_32x32x16_bf16 a[128:143], v[184:187], v[212:215], a[128:143]
	v_mfma_f32_32x32x16_bf16 a[64:79], v[184:187], v[216:219], a[64:79]
	v_mfma_f32_32x32x16_bf16 a[0:15], v[184:187], v[220:223], a[0:15]
	ds_read_b128 v[184:187], v224 offset:9248
	ds_read_b128 v[188:191], v225 offset:64
	ds_read_b128 v[192:195], v225 offset:4672
	v_lshl_add_u64 v[50:51], v[12:13], 0, s[34:35]
	v_lshl_add_u64 v[64:65], v[14:15], 0, s[34:35]
	global_load_dwordx4 v[140:143], v[50:51], off offset:384
	global_load_dwordx4 v[148:151], v[64:65], off offset:384
	s_waitcnt lgkmcnt(7)
	v_mfma_f32_32x32x16_bf16 a[208:223], v[204:207], v[208:211], a[208:223]
	v_mfma_f32_32x32x16_bf16 a[144:159], v[204:207], v[212:215], a[144:159]
	v_mfma_f32_32x32x16_bf16 a[80:95], v[204:207], v[216:219], a[80:95]
	v_mfma_f32_32x32x16_bf16 a[16:31], v[204:207], v[220:223], a[16:31]
	ds_read_b128 v[204:207], v224 offset:13856
	ds_read_b128 v[196:199], v225 offset:9280
	ds_read_b128 v[200:203], v225 offset:13888
	v_lshl_add_u64 v[50:51], v[16:17], 0, s[34:35]
	v_lshl_add_u64 v[64:65], v[18:19], 0, s[34:35]
	global_load_dwordx4 v[152:155], v[50:51], off offset:384
	global_load_dwordx4 v[156:159], v[64:65], off offset:384
	s_waitcnt lgkmcnt(5)
; template <int EPI>
; DEV void gemm_tile(CParams& p, int layer, const bf16_t* __restrict__ A, int lda, const bf16_t* __restrict__ Bt, int K, int m0, int n0, int nt, char* lds, const int swave) {
;     ...
;     COMPUTE(1, ra0, rb0, 0, more);
;     __syncthreads();
	v_mfma_f32_32x32x16_bf16 a[224:239], v[184:187], v[208:211], a[224:239]
	v_mfma_f32_32x32x16_bf16 a[160:175], v[184:187], v[212:215], a[160:175]
	v_mfma_f32_32x32x16_bf16 a[96:111], v[184:187], v[216:219], a[96:111]
	v_mfma_f32_32x32x16_bf16 a[32:47], v[184:187], v[220:223], a[32:47]
	ds_read_b128 v[184:187], v224 offset:64
	v_lshl_add_u64 v[50:51], v[20:21], 0, s[34:35]
	v_lshl_add_u64 v[64:65], v[22:23], 0, s[34:35]
	global_load_dwordx4 v[164:167], v[50:51], off offset:384
	global_load_dwordx4 v[168:171], v[64:65], off offset:384
	s_waitcnt lgkmcnt(3)
	v_mfma_f32_32x32x16_bf16 a[240:255], v[204:207], v[208:211], a[240:255]
	v_mfma_f32_32x32x16_bf16 a[176:191], v[204:207], v[212:215], a[176:191]
	v_mfma_f32_32x32x16_bf16 a[112:127], v[204:207], v[216:219], a[112:127]
	v_mfma_f32_32x32x16_bf16 a[48:63], v[204:207], v[220:223], a[48:63]
	ds_read_b128 v[204:207], v224 offset:4672
	v_lshl_add_u64 v[50:51], v[24:25], 0, s[34:35]
	v_lshl_add_u64 v[64:65], v[26:27], 0, s[34:35]
	global_load_dwordx4 v[172:175], v[50:51], off offset:384
	global_load_dwordx4 v[176:179], v[64:65], off offset:384
	s_waitcnt vmcnt(27)
	ds_write_b128 v30, v[72:75] offset:9216
	s_waitcnt vmcnt(26)
	ds_write_b128 v30, v[76:79] offset:46080
	s_waitcnt vmcnt(25)
	ds_write_b128 v30, v[80:83] offset:13824
	s_waitcnt vmcnt(24)
	ds_write_b128 v30, v[84:87] offset:50688
	s_waitcnt lgkmcnt(5)
	v_mfma_f32_32x32x16_bf16 a[192:207], v[184:187], v[188:191], a[192:207]
	v_mfma_f32_32x32x16_bf16 a[128:143], v[184:187], v[192:195], a[128:143]
	v_mfma_f32_32x32x16_bf16 a[64:79], v[184:187], v[196:199], a[64:79]
	v_mfma_f32_32x32x16_bf16 a[0:15], v[184:187], v[200:203], a[0:15]
	ds_read_b128 v[184:187], v224 offset:9280
	ds_read_b128 v[208:211], v225 offset:96
	ds_read_b128 v[212:215], v225 offset:4704
	s_waitcnt lgkmcnt(7)
	v_mfma_f32_32x32x16_bf16 a[208:223], v[204:207], v[188:191], a[208:223]
	v_mfma_f32_32x32x16_bf16 a[144:159], v[204:207], v[192:195], a[144:159]
	v_mfma_f32_32x32x16_bf16 a[80:95], v[204:207], v[196:199], a[80:95]
	v_mfma_f32_32x32x16_bf16 a[16:31], v[204:207], v[200:203], a[16:31]
	ds_read_b128 v[204:207], v224 offset:13888
	ds_read_b128 v[216:219], v225 offset:9312
	ds_read_b128 v[220:223], v225 offset:13920
	s_waitcnt lgkmcnt(5)
	v_mfma_f32_32x32x16_bf16 a[224:239], v[184:187], v[188:191], a[224:239]
	v_mfma_f32_32x32x16_bf16 a[160:175], v[184:187], v[192:195], a[160:175]
	v_mfma_f32_32x32x16_bf16 a[96:111], v[184:187], v[196:199], a[96:111]
	v_mfma_f32_32x32x16_bf16 a[32:47], v[184:187], v[200:203], a[32:47]
	ds_read_b128 v[184:187], v224 offset:96
	s_waitcnt lgkmcnt(3)
	v_mfma_f32_32x32x16_bf16 a[240:255], v[204:207], v[188:191], a[240:255]
	v_mfma_f32_32x32x16_bf16 a[176:191], v[204:207], v[192:195], a[176:191]
	v_mfma_f32_32x32x16_bf16 a[112:127], v[204:207], v[196:199], a[112:127]
	v_mfma_f32_32x32x16_bf16 a[48:63], v[204:207], v[200:203], a[48:63]
	ds_read_b128 v[204:207], v224 offset:4704
	s_waitcnt vmcnt(23)
	ds_write_b128 v30, v[88:91] offset:18432
	s_waitcnt vmcnt(22)
	ds_write_b128 v30, v[92:95] offset:55296
	s_waitcnt vmcnt(21)
	ds_write_b128 v30, v[96:99] offset:23040
	s_waitcnt vmcnt(20)
	ds_write_b128 v30, v[108:111] offset:59904
	s_waitcnt lgkmcnt(5)
	v_mfma_f32_32x32x16_bf16 a[192:207], v[184:187], v[208:211], a[192:207]
	v_mfma_f32_32x32x16_bf16 a[128:143], v[184:187], v[212:215], a[128:143]
	v_mfma_f32_32x32x16_bf16 a[64:79], v[184:187], v[216:219], a[64:79]
	v_mfma_f32_32x32x16_bf16 a[0:15], v[184:187], v[220:223], a[0:15]
	ds_read_b128 v[184:187], v224 offset:9312
	s_waitcnt lgkmcnt(5)
	v_mfma_f32_32x32x16_bf16 a[208:223], v[204:207], v[208:211], a[208:223]
	v_mfma_f32_32x32x16_bf16 a[144:159], v[204:207], v[212:215], a[144:159]
	v_mfma_f32_32x32x16_bf16 a[80:95], v[204:207], v[216:219], a[80:95]
	v_mfma_f32_32x32x16_bf16 a[16:31], v[204:207], v[220:223], a[16:31]
	ds_read_b128 v[204:207], v224 offset:13920
	s_waitcnt lgkmcnt(1)
	v_mfma_f32_32x32x16_bf16 a[224:239], v[184:187], v[208:211], a[224:239]
	v_mfma_f32_32x32x16_bf16 a[160:175], v[184:187], v[212:215], a[160:175]
	v_mfma_f32_32x32x16_bf16 a[96:111], v[184:187], v[216:219], a[96:111]
	v_mfma_f32_32x32x16_bf16 a[32:47], v[184:187], v[220:223], a[32:47]
	s_waitcnt lgkmcnt(0)
	v_mfma_f32_32x32x16_bf16 a[240:255], v[204:207], v[208:211], a[240:255]
	v_mfma_f32_32x32x16_bf16 a[176:191], v[204:207], v[212:215], a[176:191]
	v_mfma_f32_32x32x16_bf16 a[112:127], v[204:207], v[216:219], a[112:127]
	v_mfma_f32_32x32x16_bf16 a[48:63], v[204:207], v[220:223], a[48:63]
	s_waitcnt vmcnt(19)
	ds_write_b128 v30, v[124:127] offset:27648
	s_waitcnt vmcnt(18)
	ds_write_b128 v30, v[144:147] offset:64512
	s_waitcnt vmcnt(17)
	ds_write_b128 v30, v[160:163] offset:32256
	s_waitcnt vmcnt(16)
	ds_write_b128 v47, v[180:183]
	s_branch .LBB0_98

; #define GLOAD(RA, RB, kt) { _Pragma("unroll") for (int i = 0; i < 8; ++i) { const int ia = (tail && i >= 4) ? i - 4 : i; \
;     RA[i] = *(const u32x4*)(abase + ((size_t)(32 * ia) * lda + (kt) * 64) * 2 + aoff); RB[i] = *(const u32x4*)(bbase + ((size_t)(32 * i) * K + (kt) * 64) * 2 + boff); } }
; #define LWRITE(RA, RB, buf) { char* as_ = lds + (buf) * 2 * G_TILE; char* bs_ = as_ + G_TILE; _Pragma("unroll") for (int i = 0; i < 8; ++i) { *(u32x4*)(as_ + (lrow + 32 * i) * GS_B + lch * 16) = RA[i]; *(u32x4*)(bs_ + (lrow + 32 * i) * GS_B + lch * 16) = RB[i]; } }
; template <int EPI>
; DEV void gemm_tile(CParams& p, int layer, const bf16_t* __restrict__ A, int lda, const bf16_t* __restrict__ Bt, int K, int m0, int n0, int nt, char* lds, const int swave) {
;     ...
;   const char* asr = lds + (wm * 128 + lr) * GS_B + hh * 16;
;   const char* bsr = lds + G_TILE + (wn * 128 + lr) * GS_B + hh * 16;
;   char* wsw = lds + lrow * GS_B + lch * 16;
;     ...
;   GLOAD(ra0, rb0, 0); GLOAD(ra1, rb1, 1); LWRITE(ra0, rb0, 0); __syncthreads();
; #pragma unroll 1
;   for (int kt = 0; kt < nk; kt += 2) {
;     if (kt + 2 < nk) GLOAD(ra0, rb0, kt + 2);
;     COMPUTE(0, ra1, rb1, 1, true);
;     __syncthreads();
.LBB0_161:
	s_cmp_eq_u32 s86, 0
	s_cbranch_scc0 .Lzi_i2
	ds_read_b128 v[164:167], v26
	ds_read_b128 v[168:171], v26 offset:4608
	ds_read_b128 v[172:175], v26 offset:9216
	ds_read_b128 v[176:179], v26 offset:13824
	ds_read_b128 v[160:163], v25
	ds_read_b128 v[180:183], v25 offset:4608
	s_waitcnt lgkmcnt(1)
	v_mfma_f32_32x32x16_bf16 a[96:111], v[160:163], v[164:167], 0
	v_mfma_f32_32x32x16_bf16 a[0:15], v[160:163], v[168:171], 0
	v_mfma_f32_32x32x16_bf16 a[16:31], v[160:163], v[172:175], 0
	v_mfma_f32_32x32x16_bf16 a[32:47], v[160:163], v[176:179], 0
	ds_read_b128 v[160:163], v25 offset:9216
	ds_read_b128 v[184:187], v26 offset:32
	ds_read_b128 v[188:191], v26 offset:4640
	v_lshl_add_u64 v[28:29], v[2:3], 0, s[34:35]
	v_lshl_add_u64 v[30:31], v[4:5], 0, s[34:35]
	s_add_i32 s2, s100, s28
	s_lshl_b32 s44, s100, 6
	global_load_dwordx4 v[32:35], v[28:29], off
	global_load_dwordx4 v[36:39], v[30:31], off
	s_waitcnt lgkmcnt(3)
	v_mfma_f32_32x32x16_bf16 a[80:95], v[180:183], v[164:167], 0
	v_mfma_f32_32x32x16_bf16 a[48:63], v[180:183], v[168:171], 0
	v_mfma_f32_32x32x16_bf16 a[64:79], v[180:183], v[172:175], 0
	v_mfma_f32_32x32x16_bf16 a[112:127], v[180:183], v[176:179], 0
	ds_read_b128 v[180:183], v25 offset:13824
	ds_read_b128 v[192:195], v26 offset:9248
	ds_read_b128 v[196:199], v26 offset:13856
	v_lshl_add_u64 v[28:29], v[28:29], 0, s[8:9]
	v_lshl_add_u64 v[30:31], v[30:31], 0, s[8:9]
	s_lshl_b32 s2, s2, 7
	s_mov_b32 s3, s35
	global_load_dwordx4 v[40:43], v[28:29], off
	global_load_dwordx4 v[44:47], v[30:31], off
	s_waitcnt lgkmcnt(5)
	v_mfma_f32_32x32x16_bf16 a[128:143], v[160:163], v[164:167], 0
	v_mfma_f32_32x32x16_bf16 a[144:159], v[160:163], v[168:171], 0
	v_mfma_f32_32x32x16_bf16 a[160:175], v[160:163], v[172:175], 0
	v_mfma_f32_32x32x16_bf16 a[176:191], v[160:163], v[176:179], 0
	ds_read_b128 v[160:163], v25 offset:32
	v_lshl_add_u64 v[28:29], v[2:3], 0, s[2:3]
	v_lshl_add_u64 v[30:31], v[4:5], 0, s[2:3]
	s_add_i32 s2, s44, s38
	s_lshl_b32 s2, s2, 1
	global_load_dwordx4 v[48:51], v[28:29], off
	global_load_dwordx4 v[52:55], v[30:31], off
	s_waitcnt lgkmcnt(3)
	v_mfma_f32_32x32x16_bf16 a[192:207], v[180:183], v[164:167], 0
	v_mfma_f32_32x32x16_bf16 a[208:223], v[180:183], v[168:171], 0
	v_mfma_f32_32x32x16_bf16 a[224:239], v[180:183], v[172:175], 0
	v_mfma_f32_32x32x16_bf16 a[240:255], v[180:183], v[176:179], 0
	ds_read_b128 v[180:183], v25 offset:4640
	v_lshl_add_u64 v[28:29], v[2:3], 0, s[2:3]
	v_lshl_add_u64 v[30:31], v[4:5], 0, s[2:3]
	s_add_i32 s34, s34, s91
	s_add_i32 s2, s44, s39
	global_load_dwordx4 v[56:59], v[28:29], off
	global_load_dwordx4 v[60:63], v[30:31], off
	s_waitcnt vmcnt(23)
	ds_write_b128 v8, v[84:87]
	s_waitcnt vmcnt(22)
	ds_write_b128 v9, v[88:91]
	s_waitcnt vmcnt(21)
	ds_write_b128 v18, v[96:99]
	s_waitcnt vmcnt(20)
	ds_write_b128 v19, v[104:107]
	s_waitcnt lgkmcnt(5)
	v_mfma_f32_32x32x16_bf16 a[96:111], v[160:163], v[184:187], a[96:111]
	v_mfma_f32_32x32x16_bf16 a[0:15], v[160:163], v[188:191], a[0:15]
	v_mfma_f32_32x32x16_bf16 a[16:31], v[160:163], v[192:195], a[16:31]
	v_mfma_f32_32x32x16_bf16 a[32:47], v[160:163], v[196:199], a[32:47]
	ds_read_b128 v[160:163], v25 offset:9248
	ds_read_b128 v[164:167], v26 offset:64
	ds_read_b128 v[168:171], v26 offset:4672
	v_lshl_add_u64 v[28:29], v[2:3], 0, s[34:35]
	v_lshl_add_u64 v[30:31], v[4:5], 0, s[34:35]
	s_lshl_b32 s34, s2, 1
	s_add_i32 s2, s44, s68
	global_load_dwordx4 v[64:67], v[28:29], off
	global_load_dwordx4 v[68:71], v[30:31], off
	s_waitcnt lgkmcnt(7)
	v_mfma_f32_32x32x16_bf16 a[80:95], v[180:183], v[184:187], a[80:95]
	v_mfma_f32_32x32x16_bf16 a[48:63], v[180:183], v[188:191], a[48:63]
	v_mfma_f32_32x32x16_bf16 a[64:79], v[180:183], v[192:195], a[64:79]
	v_mfma_f32_32x32x16_bf16 a[112:127], v[180:183], v[196:199], a[112:127]
	ds_read_b128 v[180:183], v25 offset:13856
	ds_read_b128 v[172:175], v26 offset:9280
	ds_read_b128 v[176:179], v26 offset:13888
	v_lshl_add_u64 v[28:29], v[2:3], 0, s[34:35]
	v_lshl_add_u64 v[30:31], v[4:5], 0, s[34:35]
	s_lshl_b32 s34, s2, 1
	s_add_i32 s44, s44, s40
	global_load_dwordx4 v[72:75], v[28:29], off
	global_load_dwordx4 v[76:79], v[30:31], off
	s_waitcnt lgkmcnt(5)
	v_mfma_f32_32x32x16_bf16 a[128:143], v[160:163], v[184:187], a[128:143]
	v_mfma_f32_32x32x16_bf16 a[144:159], v[160:163], v[188:191], a[144:159]
	v_mfma_f32_32x32x16_bf16 a[160:175], v[160:163], v[192:195], a[160:175]
	v_mfma_f32_32x32x16_bf16 a[176:191], v[160:163], v[196:199], a[176:191]
	ds_read_b128 v[160:163], v25 offset:64
	v_lshl_add_u64 v[28:29], v[2:3], 0, s[34:35]
	v_lshl_add_u64 v[30:31], v[4:5], 0, s[34:35]
	s_lshl_b32 s34, s44, 1
	global_load_dwordx4 v[80:83], v[28:29], off
	global_load_dwordx4 v[92:95], v[30:31], off
	s_waitcnt lgkmcnt(3)
	v_mfma_f32_32x32x16_bf16 a[192:207], v[180:183], v[184:187], a[192:207]
	v_mfma_f32_32x32x16_bf16 a[208:223], v[180:183], v[188:191], a[208:223]
	v_mfma_f32_32x32x16_bf16 a[224:239], v[180:183], v[192:195], a[224:239]
	v_mfma_f32_32x32x16_bf16 a[240:255], v[180:183], v[196:199], a[240:255]
	ds_read_b128 v[180:183], v25 offset:4672
	v_lshl_add_u64 v[28:29], v[2:3], 0, s[34:35]
	v_lshl_add_u64 v[30:31], v[4:5], 0, s[34:35]
	global_load_dwordx4 v[100:103], v[28:29], off
	global_load_dwordx4 v[108:111], v[30:31], off
	s_waitcnt vmcnt(27)
	ds_write_b128 v14, v[112:115]
	s_waitcnt vmcnt(26)
	ds_write_b128 v15, v[116:119]
	s_waitcnt vmcnt(25)
	ds_write_b128 v16, v[120:123]
	s_waitcnt vmcnt(24)
	ds_write_b128 v17, v[124:127]
	s_waitcnt lgkmcnt(5)
; #define GLOAD(RA, RB, kt) { _Pragma("unroll") for (int i = 0; i < 8; ++i) { const int ia = (tail && i >= 4) ? i - 4 : i; \
;     RA[i] = *(const u32x4*)(abase + ((size_t)(32 * ia) * lda + (kt) * 64) * 2 + aoff); RB[i] = *(const u32x4*)(bbase + ((size_t)(32 * i) * K + (kt) * 64) * 2 + boff); } }
; #define LWRITE(RA, RB, buf) { char* as_ = lds + (buf) * 2 * G_TILE; char* bs_ = as_ + G_TILE; _Pragma("unroll") for (int i = 0; i < 8; ++i) { *(u32x4*)(as_ + (lrow + 32 * i) * GS_B + lch * 16) = RA[i]; *(u32x4*)(bs_ + (lrow + 32 * i) * GS_B + lch * 16) = RB[i]; } }
; template <int EPI>
; DEV void gemm_tile(CParams& p, int layer, const bf16_t* __restrict__ A, int lda, const bf16_t* __restrict__ Bt, int K, int m0, int n0, int nt, char* lds, const int swave) {
;     ...
;   GLOAD(ra0, rb0, 0); GLOAD(ra1, rb1, 1); LWRITE(ra0, rb0, 0); __syncthreads();
; #pragma unroll 1
;   for (int kt = 0; kt < nk; kt += 2) {
;     if (kt + 2 < nk) GLOAD(ra0, rb0, kt + 2);
;     COMPUTE(0, ra1, rb1, 1, true);
;     __syncthreads();
	v_mfma_f32_32x32x16_bf16 a[96:111], v[160:163], v[164:167], a[96:111]
	v_mfma_f32_32x32x16_bf16 a[0:15], v[160:163], v[168:171], a[0:15]
	v_mfma_f32_32x32x16_bf16 a[16:31], v[160:163], v[172:175], a[16:31]
	v_mfma_f32_32x32x16_bf16 a[32:47], v[160:163], v[176:179], a[32:47]
	ds_read_b128 v[160:163], v25 offset:9280
	ds_read_b128 v[184:187], v26 offset:96
	ds_read_b128 v[188:191], v26 offset:4704
	s_waitcnt lgkmcnt(7)
	v_mfma_f32_32x32x16_bf16 a[80:95], v[180:183], v[164:167], a[80:95]
	v_mfma_f32_32x32x16_bf16 a[48:63], v[180:183], v[168:171], a[48:63]
	v_mfma_f32_32x32x16_bf16 a[64:79], v[180:183], v[172:175], a[64:79]
	v_mfma_f32_32x32x16_bf16 a[112:127], v[180:183], v[176:179], a[112:127]
	ds_read_b128 v[180:183], v25 offset:13888
	ds_read_b128 v[192:195], v26 offset:9312
	ds_read_b128 v[196:199], v26 offset:13920
	s_waitcnt lgkmcnt(5)
	v_mfma_f32_32x32x16_bf16 a[128:143], v[160:163], v[164:167], a[128:143]
	v_mfma_f32_32x32x16_bf16 a[144:159], v[160:163], v[168:171], a[144:159]
	v_mfma_f32_32x32x16_bf16 a[160:175], v[160:163], v[172:175], a[160:175]
	v_mfma_f32_32x32x16_bf16 a[176:191], v[160:163], v[176:179], a[176:191]
	ds_read_b128 v[160:163], v25 offset:96
	s_waitcnt lgkmcnt(3)
	v_mfma_f32_32x32x16_bf16 a[192:207], v[180:183], v[164:167], a[192:207]
	v_mfma_f32_32x32x16_bf16 a[208:223], v[180:183], v[168:171], a[208:223]
	v_mfma_f32_32x32x16_bf16 a[224:239], v[180:183], v[172:175], a[224:239]
	v_mfma_f32_32x32x16_bf16 a[240:255], v[180:183], v[176:179], a[240:255]
	ds_read_b128 v[180:183], v25 offset:4704
	s_waitcnt vmcnt(23)
	ds_write_b128 v10, v[128:131]
	s_waitcnt vmcnt(22)
	ds_write_b128 v11, v[132:135]
	s_waitcnt vmcnt(21)
	ds_write_b128 v12, v[136:139]
	s_waitcnt vmcnt(20)
	ds_write_b128 v13, v[140:143]
	s_waitcnt lgkmcnt(5)
	v_mfma_f32_32x32x16_bf16 a[96:111], v[160:163], v[184:187], a[96:111]
	v_mfma_f32_32x32x16_bf16 a[0:15], v[160:163], v[188:191], a[0:15]
	v_mfma_f32_32x32x16_bf16 a[16:31], v[160:163], v[192:195], a[16:31]
	v_mfma_f32_32x32x16_bf16 a[32:47], v[160:163], v[196:199], a[32:47]
	ds_read_b128 v[160:163], v25 offset:9312
	s_waitcnt lgkmcnt(5)
	v_mfma_f32_32x32x16_bf16 a[80:95], v[180:183], v[184:187], a[80:95]
	v_mfma_f32_32x32x16_bf16 a[48:63], v[180:183], v[188:191], a[48:63]
	v_mfma_f32_32x32x16_bf16 a[64:79], v[180:183], v[192:195], a[64:79]
	v_mfma_f32_32x32x16_bf16 a[112:127], v[180:183], v[196:199], a[112:127]
	ds_read_b128 v[180:183], v25 offset:13920
	s_waitcnt lgkmcnt(1)
	v_mfma_f32_32x32x16_bf16 a[128:143], v[160:163], v[184:187], a[128:143]
	v_mfma_f32_32x32x16_bf16 a[144:159], v[160:163], v[188:191], a[144:159]
	v_mfma_f32_32x32x16_bf16 a[160:175], v[160:163], v[192:195], a[160:175]
	v_mfma_f32_32x32x16_bf16 a[176:191], v[160:163], v[196:199], a[176:191]
	s_waitcnt lgkmcnt(0)
	v_mfma_f32_32x32x16_bf16 a[192:207], v[180:183], v[184:187], a[192:207]
	v_mfma_f32_32x32x16_bf16 a[208:223], v[180:183], v[188:191], a[208:223]
	v_mfma_f32_32x32x16_bf16 a[224:239], v[180:183], v[192:195], a[224:239]
	v_mfma_f32_32x32x16_bf16 a[240:255], v[180:183], v[196:199], a[240:255]
	s_waitcnt vmcnt(19)
	ds_write_b128 v20, v[144:147]
	s_waitcnt vmcnt(18)
	ds_write_b128 v21, v[148:151]
	s_waitcnt vmcnt(17)
	ds_write_b128 v22, v[152:155]
	s_waitcnt vmcnt(16)
	ds_write_b128 v23, v[156:159]
	s_branch .LBB0_177
.Lzi_i2:
	ds_read_b128 v[164:167], v26
	ds_read_b128 v[168:171], v26 offset:4608
	ds_read_b128 v[172:175], v26 offset:9216
	ds_read_b128 v[176:179], v26 offset:13824
	ds_read_b128 v[160:163], v25
	ds_read_b128 v[180:183], v25 offset:4608
	s_waitcnt lgkmcnt(1)
	v_mfma_f32_32x32x16_bf16 a[96:111], v[160:163], v[164:167], a[96:111]
	v_mfma_f32_32x32x16_bf16 a[0:15], v[160:163], v[168:171], a[0:15]
	v_mfma_f32_32x32x16_bf16 a[16:31], v[160:163], v[172:175], a[16:31]
	v_mfma_f32_32x32x16_bf16 a[32:47], v[160:163], v[176:179], a[32:47]
	ds_read_b128 v[160:163], v25 offset:9216
	ds_read_b128 v[184:187], v26 offset:32
	ds_read_b128 v[188:191], v26 offset:4640
	v_lshl_add_u64 v[28:29], v[2:3], 0, s[34:35]
	v_lshl_add_u64 v[30:31], v[4:5], 0, s[34:35]
	s_add_i32 s2, s100, s28
	s_lshl_b32 s44, s100, 6
	global_load_dwordx4 v[32:35], v[28:29], off
	global_load_dwordx4 v[36:39], v[30:31], off
	s_waitcnt lgkmcnt(3)
	v_mfma_f32_32x32x16_bf16 a[80:95], v[180:183], v[164:167], a[80:95]
	v_mfma_f32_32x32x16_bf16 a[48:63], v[180:183], v[168:171], a[48:63]
	v_mfma_f32_32x32x16_bf16 a[64:79], v[180:183], v[172:175], a[64:79]
	v_mfma_f32_32x32x16_bf16 a[112:127], v[180:183], v[176:179], a[112:127]
	ds_read_b128 v[180:183], v25 offset:13824
	ds_read_b128 v[192:195], v26 offset:9248
	ds_read_b128 v[196:199], v26 offset:13856
	v_lshl_add_u64 v[28:29], v[28:29], 0, s[8:9]
	v_lshl_add_u64 v[30:31], v[30:31], 0, s[8:9]
	s_lshl_b32 s2, s2, 7
	s_mov_b32 s3, s35
	global_load_dwordx4 v[40:43], v[28:29], off
	global_load_dwordx4 v[44:47], v[30:31], off
	s_waitcnt lgkmcnt(5)
	v_mfma_f32_32x32x16_bf16 a[128:143], v[160:163], v[164:167], a[128:143]
	v_mfma_f32_32x32x16_bf16 a[144:159], v[160:163], v[168:171], a[144:159]
	v_mfma_f32_32x32x16_bf16 a[160:175], v[160:163], v[172:175], a[160:175]
	v_mfma_f32_32x32x16_bf16 a[176:191], v[160:163], v[176:179], a[176:191]
	ds_read_b128 v[160:163], v25 offset:32
	v_lshl_add_u64 v[28:29], v[2:3], 0, s[2:3]
	v_lshl_add_u64 v[30:31], v[4:5], 0, s[2:3]
	s_add_i32 s2, s44, s38
	s_lshl_b32 s2, s2, 1
	global_load_dwordx4 v[48:51], v[28:29], off
	global_load_dwordx4 v[52:55], v[30:31], off
	s_waitcnt lgkmcnt(3)
; #define GLOAD(RA, RB, kt) { _Pragma("unroll") for (int i = 0; i < 8; ++i) { const int ia = (tail && i >= 4) ? i - 4 : i; \
;     RA[i] = *(const u32x4*)(abase + ((size_t)(32 * ia) * lda + (kt) * 64) * 2 + aoff); RB[i] = *(const u32x4*)(bbase + ((size_t)(32 * i) * K + (kt) * 64) * 2 + boff); } }
; #define LWRITE(RA, RB, buf) { char* as_ = lds + (buf) * 2 * G_TILE; char* bs_ = as_ + G_TILE; _Pragma("unroll") for (int i = 0; i < 8; ++i) { *(u32x4*)(as_ + (lrow + 32 * i) * GS_B + lch * 16) = RA[i]; *(u32x4*)(bs_ + (lrow + 32 * i) * GS_B + lch * 16) = RB[i]; } }
; template <int EPI>
; DEV void gemm_tile(CParams& p, int layer, const bf16_t* __restrict__ A, int lda, const bf16_t* __restrict__ Bt, int K, int m0, int n0, int nt, char* lds, const int swave) {
;     ...
;   GLOAD(ra0, rb0, 0); GLOAD(ra1, rb1, 1); LWRITE(ra0, rb0, 0); __syncthreads();
; #pragma unroll 1
;   for (int kt = 0; kt < nk; kt += 2) {
;     if (kt + 2 < nk) GLOAD(ra0, rb0, kt + 2);
;     COMPUTE(0, ra1, rb1, 1, true);
;     __syncthreads();
	v_mfma_f32_32x32x16_bf16 a[192:207], v[180:183], v[164:167], a[192:207]
	v_mfma_f32_32x32x16_bf16 a[208:223], v[180:183], v[168:171], a[208:223]
	v_mfma_f32_32x32x16_bf16 a[224:239], v[180:183], v[172:175], a[224:239]
	v_mfma_f32_32x32x16_bf16 a[240:255], v[180:183], v[176:179], a[240:255]
	ds_read_b128 v[180:183], v25 offset:4640
	v_lshl_add_u64 v[28:29], v[2:3], 0, s[2:3]
	v_lshl_add_u64 v[30:31], v[4:5], 0, s[2:3]
	s_add_i32 s34, s34, s91
	s_add_i32 s2, s44, s39
	global_load_dwordx4 v[56:59], v[28:29], off
	global_load_dwordx4 v[60:63], v[30:31], off
	s_waitcnt vmcnt(23)
	ds_write_b128 v8, v[84:87]
	s_waitcnt vmcnt(22)
	ds_write_b128 v9, v[88:91]
	s_waitcnt vmcnt(21)
	ds_write_b128 v18, v[96:99]
	s_waitcnt vmcnt(20)
	ds_write_b128 v19, v[104:107]
	s_waitcnt lgkmcnt(5)
	v_mfma_f32_32x32x16_bf16 a[96:111], v[160:163], v[184:187], a[96:111]
	v_mfma_f32_32x32x16_bf16 a[0:15], v[160:163], v[188:191], a[0:15]
	v_mfma_f32_32x32x16_bf16 a[16:31], v[160:163], v[192:195], a[16:31]
	v_mfma_f32_32x32x16_bf16 a[32:47], v[160:163], v[196:199], a[32:47]
	ds_read_b128 v[160:163], v25 offset:9248
	ds_read_b128 v[164:167], v26 offset:64
	ds_read_b128 v[168:171], v26 offset:4672
	v_lshl_add_u64 v[28:29], v[2:3], 0, s[34:35]
	v_lshl_add_u64 v[30:31], v[4:5], 0, s[34:35]
	s_lshl_b32 s34, s2, 1
	s_add_i32 s2, s44, s68
	global_load_dwordx4 v[64:67], v[28:29], off
	global_load_dwordx4 v[68:71], v[30:31], off
	s_waitcnt lgkmcnt(7)
	v_mfma_f32_32x32x16_bf16 a[80:95], v[180:183], v[184:187], a[80:95]
	v_mfma_f32_32x32x16_bf16 a[48:63], v[180:183], v[188:191], a[48:63]
	v_mfma_f32_32x32x16_bf16 a[64:79], v[180:183], v[192:195], a[64:79]
	v_mfma_f32_32x32x16_bf16 a[112:127], v[180:183], v[196:199], a[112:127]
	ds_read_b128 v[180:183], v25 offset:13856
	ds_read_b128 v[172:175], v26 offset:9280
	ds_read_b128 v[176:179], v26 offset:13888
	v_lshl_add_u64 v[28:29], v[2:3], 0, s[34:35]
	v_lshl_add_u64 v[30:31], v[4:5], 0, s[34:35]
	s_lshl_b32 s34, s2, 1
	s_add_i32 s44, s44, s40
	global_load_dwordx4 v[72:75], v[28:29], off
	global_load_dwordx4 v[76:79], v[30:31], off
	s_waitcnt lgkmcnt(5)
	v_mfma_f32_32x32x16_bf16 a[128:143], v[160:163], v[184:187], a[128:143]
	v_mfma_f32_32x32x16_bf16 a[144:159], v[160:163], v[188:191], a[144:159]
	v_mfma_f32_32x32x16_bf16 a[160:175], v[160:163], v[192:195], a[160:175]
	v_mfma_f32_32x32x16_bf16 a[176:191], v[160:163], v[196:199], a[176:191]
	ds_read_b128 v[160:163], v25 offset:64
	v_lshl_add_u64 v[28:29], v[2:3], 0, s[34:35]
	v_lshl_add_u64 v[30:31], v[4:5], 0, s[34:35]
	s_lshl_b32 s34, s44, 1
	global_load_dwordx4 v[80:83], v[28:29], off
	global_load_dwordx4 v[92:95], v[30:31], off
	s_waitcnt lgkmcnt(3)
	v_mfma_f32_32x32x16_bf16 a[192:207], v[180:183], v[184:187], a[192:207]
	v_mfma_f32_32x32x16_bf16 a[208:223], v[180:183], v[188:191], a[208:223]
	v_mfma_f32_32x32x16_bf16 a[224:239], v[180:183], v[192:195], a[224:239]
	v_mfma_f32_32x32x16_bf16 a[240:255], v[180:183], v[196:199], a[240:255]
	ds_read_b128 v[180:183], v25 offset:4672
	v_lshl_add_u64 v[28:29], v[2:3], 0, s[34:35]
	v_lshl_add_u64 v[30:31], v[4:5], 0, s[34:35]
	global_load_dwordx4 v[100:103], v[28:29], off
	global_load_dwordx4 v[108:111], v[30:31], off
	s_waitcnt vmcnt(27)
	ds_write_b128 v14, v[112:115]
	s_waitcnt vmcnt(26)
	ds_write_b128 v15, v[116:119]
	s_waitcnt vmcnt(25)
	ds_write_b128 v16, v[120:123]
	s_waitcnt vmcnt(24)
	ds_write_b128 v17, v[124:127]
	s_waitcnt lgkmcnt(5)
	v_mfma_f32_32x32x16_bf16 a[96:111], v[160:163], v[164:167], a[96:111]
	v_mfma_f32_32x32x16_bf16 a[0:15], v[160:163], v[168:171], a[0:15]
	v_mfma_f32_32x32x16_bf16 a[16:31], v[160:163], v[172:175], a[16:31]
	v_mfma_f32_32x32x16_bf16 a[32:47], v[160:163], v[176:179], a[32:47]
	ds_read_b128 v[160:163], v25 offset:9280
	ds_read_b128 v[184:187], v26 offset:96
	ds_read_b128 v[188:191], v26 offset:4704
	s_waitcnt lgkmcnt(7)
	v_mfma_f32_32x32x16_bf16 a[80:95], v[180:183], v[164:167], a[80:95]
	v_mfma_f32_32x32x16_bf16 a[48:63], v[180:183], v[168:171], a[48:63]
	v_mfma_f32_32x32x16_bf16 a[64:79], v[180:183], v[172:175], a[64:79]
	v_mfma_f32_32x32x16_bf16 a[112:127], v[180:183], v[176:179], a[112:127]
	ds_read_b128 v[180:183], v25 offset:13888
	ds_read_b128 v[192:195], v26 offset:9312
	ds_read_b128 v[196:199], v26 offset:13920
	s_waitcnt lgkmcnt(5)
	v_mfma_f32_32x32x16_bf16 a[128:143], v[160:163], v[164:167], a[128:143]
	v_mfma_f32_32x32x16_bf16 a[144:159], v[160:163], v[168:171], a[144:159]
	v_mfma_f32_32x32x16_bf16 a[160:175], v[160:163], v[172:175], a[160:175]
	v_mfma_f32_32x32x16_bf16 a[176:191], v[160:163], v[176:179], a[176:191]
	ds_read_b128 v[160:163], v25 offset:96
	s_waitcnt lgkmcnt(3)
	v_mfma_f32_32x32x16_bf16 a[192:207], v[180:183], v[164:167], a[192:207]
	v_mfma_f32_32x32x16_bf16 a[208:223], v[180:183], v[168:171], a[208:223]
	v_mfma_f32_32x32x16_bf16 a[224:239], v[180:183], v[172:175], a[224:239]
	v_mfma_f32_32x32x16_bf16 a[240:255], v[180:183], v[176:179], a[240:255]
	ds_read_b128 v[180:183], v25 offset:4704
	s_waitcnt vmcnt(23)
	ds_write_b128 v10, v[128:131]
	s_waitcnt vmcnt(22)
	ds_write_b128 v11, v[132:135]
	s_waitcnt vmcnt(21)
	ds_write_b128 v12, v[136:139]
	s_waitcnt vmcnt(20)
	ds_write_b128 v13, v[140:143]
	s_waitcnt lgkmcnt(5)
	v_mfma_f32_32x32x16_bf16 a[96:111], v[160:163], v[184:187], a[96:111]
	v_mfma_f32_32x32x16_bf16 a[0:15], v[160:163], v[188:191], a[0:15]
	v_mfma_f32_32x32x16_bf16 a[16:31], v[160:163], v[192:195], a[16:31]
	v_mfma_f32_32x32x16_bf16 a[32:47], v[160:163], v[196:199], a[32:47]
	ds_read_b128 v[160:163], v25 offset:9312
	s_waitcnt lgkmcnt(5)
	v_mfma_f32_32x32x16_bf16 a[80:95], v[180:183], v[184:187], a[80:95]
	v_mfma_f32_32x32x16_bf16 a[48:63], v[180:183], v[188:191], a[48:63]
	v_mfma_f32_32x32x16_bf16 a[64:79], v[180:183], v[192:195], a[64:79]
	v_mfma_f32_32x32x16_bf16 a[112:127], v[180:183], v[196:199], a[112:127]
	ds_read_b128 v[180:183], v25 offset:13920
	s_waitcnt lgkmcnt(1)
	v_mfma_f32_32x32x16_bf16 a[128:143], v[160:163], v[184:187], a[128:143]
	v_mfma_f32_32x32x16_bf16 a[144:159], v[160:163], v[188:191], a[144:159]
	v_mfma_f32_32x32x16_bf16 a[160:175], v[160:163], v[192:195], a[160:175]
	v_mfma_f32_32x32x16_bf16 a[176:191], v[160:163], v[196:199], a[176:191]
	s_waitcnt lgkmcnt(0)
	v_mfma_f32_32x32x16_bf16 a[192:207], v[180:183], v[184:187], a[192:207]
	v_mfma_f32_32x32x16_bf16 a[208:223], v[180:183], v[188:191], a[208:223]
	v_mfma_f32_32x32x16_bf16 a[224:239], v[180:183], v[192:195], a[224:239]
	v_mfma_f32_32x32x16_bf16 a[240:255], v[180:183], v[196:199], a[240:255]
	s_waitcnt vmcnt(19)
	ds_write_b128 v20, v[144:147]
	s_waitcnt vmcnt(18)
	ds_write_b128 v21, v[148:151]
	s_waitcnt vmcnt(17)
	ds_write_b128 v22, v[152:155]
	s_waitcnt vmcnt(16)
	ds_write_b128 v23, v[156:159]

; #define GLOAD(RA, RB, kt) { _Pragma("unroll") for (int i = 0; i < 8; ++i) { const int ia = (tail && i >= 4) ? i - 4 : i; \
;     RA[i] = *(const u32x4*)(abase + ((size_t)(32 * ia) * lda + (kt) * 64) * 2 + aoff); RB[i] = *(const u32x4*)(bbase + ((size_t)(32 * i) * K + (kt) * 64) * 2 + boff); } }
; template <int EPI>
; DEV void gemm_tile(CParams& p, int layer, const bf16_t* __restrict__ A, int lda, const bf16_t* __restrict__ Bt, int K, int m0, int n0, int nt, char* lds, const int swave) {
;     ...
;     const bool more = kt + 2 < nk;
;     if (kt + 3 < nk) GLOAD(ra1, rb1, kt + 3);
;     COMPUTE(1, ra0, rb0, 0, more);
;     __syncthreads();
.LBB0_179:
	v_add_u32_e32 v200, 0x1b000, v6
	v_add_u32_e32 v201, 0x12000, v26
	s_andn2_b64 vcc, exec, s[60:61]
	s_cbranch_vccnz .Lpg_i2_nomore
	ds_read_b128 v[164:167], v201
	ds_read_b128 v[168:171], v201 offset:4608
	ds_read_b128 v[172:175], v201 offset:9216
	ds_read_b128 v[176:179], v201 offset:13824
	ds_read_b128 v[160:163], v200
	ds_read_b128 v[180:183], v200 offset:4608
	s_waitcnt lgkmcnt(1)
	v_mfma_f32_32x32x16_bf16 a[96:111], v[160:163], v[164:167], a[96:111]
	v_mfma_f32_32x32x16_bf16 a[0:15], v[160:163], v[168:171], a[0:15]
	v_mfma_f32_32x32x16_bf16 a[16:31], v[160:163], v[172:175], a[16:31]
	v_mfma_f32_32x32x16_bf16 a[32:47], v[160:163], v[176:179], a[32:47]
	ds_read_b128 v[160:163], v200 offset:9216
	ds_read_b128 v[184:187], v201 offset:32
	ds_read_b128 v[188:191], v201 offset:4640
	s_lshl_b32 s34, s2, 7
	s_lshl_b32 s44, s2, 6
	v_lshl_add_u64 v[28:29], v[2:3], 0, s[34:35]
	v_lshl_add_u64 v[30:31], v[4:5], 0, s[34:35]
	s_add_i32 s2, s2, s28
	global_load_dwordx4 v[84:87], v[28:29], off
	global_load_dwordx4 v[88:91], v[30:31], off
	s_waitcnt lgkmcnt(3)
	v_mfma_f32_32x32x16_bf16 a[80:95], v[180:183], v[164:167], a[80:95]
	v_mfma_f32_32x32x16_bf16 a[48:63], v[180:183], v[168:171], a[48:63]
	v_mfma_f32_32x32x16_bf16 a[64:79], v[180:183], v[172:175], a[64:79]
	v_mfma_f32_32x32x16_bf16 a[112:127], v[180:183], v[176:179], a[112:127]
	ds_read_b128 v[180:183], v200 offset:13824
	ds_read_b128 v[192:195], v201 offset:9248
	ds_read_b128 v[196:199], v201 offset:13856
	v_lshl_add_u64 v[28:29], v[28:29], 0, s[8:9]
	v_lshl_add_u64 v[30:31], v[30:31], 0, s[8:9]
	s_lshl_b32 s2, s2, 7
	s_mov_b32 s3, s35
	global_load_dwordx4 v[96:99], v[28:29], off
	global_load_dwordx4 v[104:107], v[30:31], off
	s_waitcnt lgkmcnt(5)
	v_mfma_f32_32x32x16_bf16 a[128:143], v[160:163], v[164:167], a[128:143]
	v_mfma_f32_32x32x16_bf16 a[144:159], v[160:163], v[168:171], a[144:159]
	v_mfma_f32_32x32x16_bf16 a[160:175], v[160:163], v[172:175], a[160:175]
	v_mfma_f32_32x32x16_bf16 a[176:191], v[160:163], v[176:179], a[176:191]
	ds_read_b128 v[160:163], v200 offset:32
	v_lshl_add_u64 v[28:29], v[2:3], 0, s[2:3]
	v_lshl_add_u64 v[30:31], v[4:5], 0, s[2:3]
	s_add_i32 s2, s44, s38
	s_lshl_b32 s2, s2, 1
	global_load_dwordx4 v[112:115], v[28:29], off
	global_load_dwordx4 v[116:119], v[30:31], off
	s_waitcnt lgkmcnt(3)
	v_mfma_f32_32x32x16_bf16 a[192:207], v[180:183], v[164:167], a[192:207]
	v_mfma_f32_32x32x16_bf16 a[208:223], v[180:183], v[168:171], a[208:223]
	v_mfma_f32_32x32x16_bf16 a[224:239], v[180:183], v[172:175], a[224:239]
	v_mfma_f32_32x32x16_bf16 a[240:255], v[180:183], v[176:179], a[240:255]
	ds_read_b128 v[180:183], v200 offset:4640
	v_lshl_add_u64 v[28:29], v[2:3], 0, s[2:3]
	v_lshl_add_u64 v[30:31], v[4:5], 0, s[2:3]
	s_add_i32 s34, s34, s91
	s_add_i32 s2, s44, s39
	global_load_dwordx4 v[120:123], v[28:29], off
	global_load_dwordx4 v[124:127], v[30:31], off
	s_waitcnt vmcnt(23)
	ds_write_b128 v7, v[32:35]
	s_waitcnt vmcnt(22)
	ds_write_b128 v7, v[36:39] offset:36864
	s_waitcnt vmcnt(21)
	ds_write_b128 v7, v[40:43] offset:4608
	s_waitcnt vmcnt(20)
	ds_write_b128 v7, v[44:47] offset:41472
	s_waitcnt lgkmcnt(5)
	v_mfma_f32_32x32x16_bf16 a[96:111], v[160:163], v[184:187], a[96:111]
	v_mfma_f32_32x32x16_bf16 a[0:15], v[160:163], v[188:191], a[0:15]
	v_mfma_f32_32x32x16_bf16 a[16:31], v[160:163], v[192:195], a[16:31]
	v_mfma_f32_32x32x16_bf16 a[32:47], v[160:163], v[196:199], a[32:47]
	ds_read_b128 v[160:163], v200 offset:9248
	ds_read_b128 v[164:167], v201 offset:64
	ds_read_b128 v[168:171], v201 offset:4672
	v_lshl_add_u64 v[28:29], v[2:3], 0, s[34:35]
	v_lshl_add_u64 v[30:31], v[4:5], 0, s[34:35]
	s_lshl_b32 s34, s2, 1
	s_add_i32 s2, s44, s68
	global_load_dwordx4 v[128:131], v[28:29], off
	global_load_dwordx4 v[132:135], v[30:31], off
	s_waitcnt lgkmcnt(7)
	v_mfma_f32_32x32x16_bf16 a[80:95], v[180:183], v[184:187], a[80:95]
	v_mfma_f32_32x32x16_bf16 a[48:63], v[180:183], v[188:191], a[48:63]
	v_mfma_f32_32x32x16_bf16 a[64:79], v[180:183], v[192:195], a[64:79]
	v_mfma_f32_32x32x16_bf16 a[112:127], v[180:183], v[196:199], a[112:127]
	ds_read_b128 v[180:183], v200 offset:13856
	ds_read_b128 v[172:175], v201 offset:9280
	ds_read_b128 v[176:179], v201 offset:13888
	v_lshl_add_u64 v[28:29], v[2:3], 0, s[34:35]
	v_lshl_add_u64 v[30:31], v[4:5], 0, s[34:35]
	s_lshl_b32 s34, s2, 1
	s_add_i32 s44, s44, s40
	global_load_dwordx4 v[136:139], v[28:29], off
	global_load_dwordx4 v[140:143], v[30:31], off
	s_waitcnt lgkmcnt(5)
; template <int EPI>
; DEV void gemm_tile(CParams& p, int layer, const bf16_t* __restrict__ A, int lda, const bf16_t* __restrict__ Bt, int K, int m0, int n0, int nt, char* lds, const int swave) {
;     ...
;     COMPUTE(1, ra0, rb0, 0, more);
;     __syncthreads();
	v_mfma_f32_32x32x16_bf16 a[128:143], v[160:163], v[184:187], a[128:143]
	v_mfma_f32_32x32x16_bf16 a[144:159], v[160:163], v[188:191], a[144:159]
	v_mfma_f32_32x32x16_bf16 a[160:175], v[160:163], v[192:195], a[160:175]
	v_mfma_f32_32x32x16_bf16 a[176:191], v[160:163], v[196:199], a[176:191]
	ds_read_b128 v[160:163], v200 offset:64
	v_lshl_add_u64 v[28:29], v[2:3], 0, s[34:35]
	v_lshl_add_u64 v[30:31], v[4:5], 0, s[34:35]
	s_lshl_b32 s34, s44, 1
	global_load_dwordx4 v[144:147], v[28:29], off
	global_load_dwordx4 v[148:151], v[30:31], off
	s_waitcnt lgkmcnt(3)
	v_mfma_f32_32x32x16_bf16 a[192:207], v[180:183], v[184:187], a[192:207]
	v_mfma_f32_32x32x16_bf16 a[208:223], v[180:183], v[188:191], a[208:223]
	v_mfma_f32_32x32x16_bf16 a[224:239], v[180:183], v[192:195], a[224:239]
	v_mfma_f32_32x32x16_bf16 a[240:255], v[180:183], v[196:199], a[240:255]
	ds_read_b128 v[180:183], v200 offset:4672
	v_lshl_add_u64 v[28:29], v[2:3], 0, s[34:35]
	v_lshl_add_u64 v[30:31], v[4:5], 0, s[34:35]
	global_load_dwordx4 v[152:155], v[28:29], off
	global_load_dwordx4 v[156:159], v[30:31], off
	s_waitcnt vmcnt(27)
	ds_write_b128 v7, v[48:51] offset:9216
	s_waitcnt vmcnt(26)
	ds_write_b128 v7, v[52:55] offset:46080
	s_waitcnt vmcnt(25)
	ds_write_b128 v7, v[56:59] offset:13824
	s_waitcnt vmcnt(24)
	ds_write_b128 v7, v[60:63] offset:50688
	s_waitcnt lgkmcnt(5)
	v_mfma_f32_32x32x16_bf16 a[96:111], v[160:163], v[164:167], a[96:111]
	v_mfma_f32_32x32x16_bf16 a[0:15], v[160:163], v[168:171], a[0:15]
	v_mfma_f32_32x32x16_bf16 a[16:31], v[160:163], v[172:175], a[16:31]
	v_mfma_f32_32x32x16_bf16 a[32:47], v[160:163], v[176:179], a[32:47]
	ds_read_b128 v[160:163], v200 offset:9280
	ds_read_b128 v[184:187], v201 offset:96
	ds_read_b128 v[188:191], v201 offset:4704
	s_waitcnt lgkmcnt(7)
	v_mfma_f32_32x32x16_bf16 a[80:95], v[180:183], v[164:167], a[80:95]
	v_mfma_f32_32x32x16_bf16 a[48:63], v[180:183], v[168:171], a[48:63]
	v_mfma_f32_32x32x16_bf16 a[64:79], v[180:183], v[172:175], a[64:79]
	v_mfma_f32_32x32x16_bf16 a[112:127], v[180:183], v[176:179], a[112:127]
	ds_read_b128 v[180:183], v200 offset:13888
	ds_read_b128 v[192:195], v201 offset:9312
	ds_read_b128 v[196:199], v201 offset:13920
	s_waitcnt lgkmcnt(5)
	v_mfma_f32_32x32x16_bf16 a[128:143], v[160:163], v[164:167], a[128:143]
	v_mfma_f32_32x32x16_bf16 a[144:159], v[160:163], v[168:171], a[144:159]
	v_mfma_f32_32x32x16_bf16 a[160:175], v[160:163], v[172:175], a[160:175]
	v_mfma_f32_32x32x16_bf16 a[176:191], v[160:163], v[176:179], a[176:191]
	ds_read_b128 v[160:163], v200 offset:96
	s_waitcnt lgkmcnt(3)
	v_mfma_f32_32x32x16_bf16 a[192:207], v[180:183], v[164:167], a[192:207]
	v_mfma_f32_32x32x16_bf16 a[208:223], v[180:183], v[168:171], a[208:223]
	v_mfma_f32_32x32x16_bf16 a[224:239], v[180:183], v[172:175], a[224:239]
	v_mfma_f32_32x32x16_bf16 a[240:255], v[180:183], v[176:179], a[240:255]
	ds_read_b128 v[180:183], v200 offset:4704
	s_waitcnt vmcnt(23)
	ds_write_b128 v7, v[64:67] offset:18432
	s_waitcnt vmcnt(22)
	ds_write_b128 v7, v[68:71] offset:55296
	s_waitcnt vmcnt(21)
	ds_write_b128 v7, v[72:75] offset:23040
	s_waitcnt vmcnt(20)
	ds_write_b128 v7, v[76:79] offset:59904
	s_waitcnt lgkmcnt(5)
	v_mfma_f32_32x32x16_bf16 a[96:111], v[160:163], v[184:187], a[96:111]
	v_mfma_f32_32x32x16_bf16 a[0:15], v[160:163], v[188:191], a[0:15]
	v_mfma_f32_32x32x16_bf16 a[16:31], v[160:163], v[192:195], a[16:31]
	v_mfma_f32_32x32x16_bf16 a[32:47], v[160:163], v[196:199], a[32:47]
	ds_read_b128 v[160:163], v200 offset:9312
	s_waitcnt lgkmcnt(5)
	v_mfma_f32_32x32x16_bf16 a[80:95], v[180:183], v[184:187], a[80:95]
	v_mfma_f32_32x32x16_bf16 a[48:63], v[180:183], v[188:191], a[48:63]
	v_mfma_f32_32x32x16_bf16 a[64:79], v[180:183], v[192:195], a[64:79]
	v_mfma_f32_32x32x16_bf16 a[112:127], v[180:183], v[196:199], a[112:127]
	ds_read_b128 v[180:183], v200 offset:13920
	s_waitcnt lgkmcnt(1)
	v_mfma_f32_32x32x16_bf16 a[128:143], v[160:163], v[184:187], a[128:143]
	v_mfma_f32_32x32x16_bf16 a[144:159], v[160:163], v[188:191], a[144:159]
	v_mfma_f32_32x32x16_bf16 a[160:175], v[160:163], v[192:195], a[160:175]
	v_mfma_f32_32x32x16_bf16 a[176:191], v[160:163], v[196:199], a[176:191]
	s_waitcnt lgkmcnt(0)
	v_mfma_f32_32x32x16_bf16 a[192:207], v[180:183], v[184:187], a[192:207]
	v_mfma_f32_32x32x16_bf16 a[208:223], v[180:183], v[188:191], a[208:223]
	v_mfma_f32_32x32x16_bf16 a[224:239], v[180:183], v[192:195], a[224:239]
	v_mfma_f32_32x32x16_bf16 a[240:255], v[180:183], v[196:199], a[240:255]
	s_waitcnt vmcnt(19)
	ds_write_b128 v7, v[80:83] offset:27648
	s_waitcnt vmcnt(18)
	ds_write_b128 v7, v[92:95] offset:64512
	s_waitcnt vmcnt(17)
	ds_write_b128 v7, v[100:103] offset:32256
	s_waitcnt vmcnt(16)
	ds_write_b128 v24, v[108:111]
	s_branch .LBB0_158

; #define GLOAD(RA, RB, kt) { _Pragma("unroll") for (int i = 0; i < 8; ++i) { const int ia = (tail && i >= 4) ? i - 4 : i; \
;     RA[i] = *(const u32x4*)(abase + ((size_t)(32 * ia) * lda + (kt) * 64) * 2 + aoff); RB[i] = *(const u32x4*)(bbase + ((size_t)(32 * i) * K + (kt) * 64) * 2 + boff); } }
; #define LWRITE(RA, RB, buf) { char* as_ = lds + (buf) * 2 * G_TILE; char* bs_ = as_ + G_TILE; _Pragma("unroll") for (int i = 0; i < 8; ++i) { *(u32x4*)(as_ + (lrow + 32 * i) * GS_B + lch * 16) = RA[i]; *(u32x4*)(bs_ + (lrow + 32 * i) * GS_B + lch * 16) = RB[i]; } }
; template <int EPI>
; DEV void gemm_tile(CParams& p, int layer, const bf16_t* __restrict__ A, int lda, const bf16_t* __restrict__ Bt, int K, int m0, int n0, int nt, char* lds, const int swave) {
;     ...
;   const char* asr = lds + (wm * 128 + lr) * GS_B + hh * 16;
;   const char* bsr = lds + G_TILE + (wn * 128 + lr) * GS_B + hh * 16;
;   char* wsw = lds + lrow * GS_B + lch * 16;
;     ...
;   GLOAD(ra0, rb0, 0); GLOAD(ra1, rb1, 1); LWRITE(ra0, rb0, 0); __syncthreads();
; #pragma unroll 1
;   for (int kt = 0; kt < nk; kt += 2) {
;     if (kt + 2 < nk) GLOAD(ra0, rb0, kt + 2);
;     COMPUTE(0, ra1, rb1, 1, true);
;     __syncthreads();
.LBB0_921:
	s_cmp_eq_u32 s42, 0
	s_cbranch_scc0 .Lzi_i3
	ds_read_b128 v[184:187], v45
	ds_read_b128 v[188:191], v45 offset:4608
	ds_read_b128 v[192:195], v45 offset:9216
	ds_read_b128 v[196:199], v45 offset:13824
	ds_read_b128 v[180:183], v49
	ds_read_b128 v[204:207], v49 offset:4608
	s_waitcnt lgkmcnt(1)
	v_mfma_f32_32x32x16_bf16 a[0:15], v[180:183], v[184:187], 0
	v_mfma_f32_32x32x16_bf16 a[16:31], v[180:183], v[188:191], 0
	v_mfma_f32_32x32x16_bf16 a[32:47], v[180:183], v[192:195], 0
	v_mfma_f32_32x32x16_bf16 a[48:63], v[180:183], v[196:199], 0
	ds_read_b128 v[180:183], v49 offset:9216
	ds_read_b128 v[208:211], v45 offset:32
	ds_read_b128 v[212:215], v45 offset:4640
	v_lshl_add_u64 v[50:51], v[0:1], 0, s[34:35]
	global_load_dwordx4 v[52:55], v[50:51], off
	v_lshl_add_u64 v[50:51], v[2:3], 0, s[34:35]
	s_or_b32 s2, s34, 0x10000
	s_mov_b32 s3, s35
	global_load_dwordx4 v[56:59], v[50:51], off
	s_waitcnt lgkmcnt(3)
	v_mfma_f32_32x32x16_bf16 a[64:79], v[204:207], v[184:187], 0
	v_mfma_f32_32x32x16_bf16 a[80:95], v[204:207], v[188:191], 0
	v_mfma_f32_32x32x16_bf16 a[96:111], v[204:207], v[192:195], 0
	v_mfma_f32_32x32x16_bf16 a[112:127], v[204:207], v[196:199], 0
	ds_read_b128 v[204:207], v49 offset:13824
	ds_read_b128 v[216:219], v45 offset:9248
	ds_read_b128 v[220:223], v45 offset:13856
	v_lshl_add_u64 v[50:51], v[0:1], 0, s[2:3]
	global_load_dwordx4 v[60:63], v[50:51], off
	v_lshl_add_u64 v[50:51], v[2:3], 0, s[2:3]
	s_or_b32 s2, s34, 0x20000
	global_load_dwordx4 v[64:67], v[50:51], off
	s_waitcnt lgkmcnt(5)
	v_mfma_f32_32x32x16_bf16 a[128:143], v[180:183], v[184:187], 0
	v_mfma_f32_32x32x16_bf16 a[144:159], v[180:183], v[188:191], 0
	v_mfma_f32_32x32x16_bf16 a[160:175], v[180:183], v[192:195], 0
	v_mfma_f32_32x32x16_bf16 a[176:191], v[180:183], v[196:199], 0
	ds_read_b128 v[180:183], v49 offset:32
	v_lshl_add_u64 v[50:51], v[0:1], 0, s[2:3]
	global_load_dwordx4 v[68:71], v[50:51], off
	v_lshl_add_u64 v[50:51], v[2:3], 0, s[2:3]
	s_or_b32 s2, s34, 0x30000
	global_load_dwordx4 v[72:75], v[50:51], off
	s_waitcnt lgkmcnt(3)
	v_mfma_f32_32x32x16_bf16 a[192:207], v[204:207], v[184:187], 0
	v_mfma_f32_32x32x16_bf16 a[208:223], v[204:207], v[188:191], 0
	v_mfma_f32_32x32x16_bf16 a[224:239], v[204:207], v[192:195], 0
	v_mfma_f32_32x32x16_bf16 a[240:255], v[204:207], v[196:199], 0
	ds_read_b128 v[204:207], v49 offset:4640
	v_lshl_add_u64 v[50:51], v[0:1], 0, s[2:3]
	global_load_dwordx4 v[76:79], v[50:51], off
	v_lshl_add_u64 v[50:51], v[2:3], 0, s[2:3]
	s_or_b32 s2, s34, 0x40000
	global_load_dwordx4 v[80:83], v[50:51], off
	s_waitcnt vmcnt(23)
	ds_write_b128 v31, v[104:107]
	s_waitcnt vmcnt(22)
	ds_write_b128 v32, v[108:111]
	s_waitcnt vmcnt(21)
	ds_write_b128 v41, v[96:99]
	s_waitcnt vmcnt(20)
	ds_write_b128 v42, v[100:103]
	s_waitcnt lgkmcnt(5)
	v_mfma_f32_32x32x16_bf16 a[0:15], v[180:183], v[208:211], a[0:15]
	v_mfma_f32_32x32x16_bf16 a[16:31], v[180:183], v[212:215], a[16:31]
	v_mfma_f32_32x32x16_bf16 a[32:47], v[180:183], v[216:219], a[32:47]
	v_mfma_f32_32x32x16_bf16 a[48:63], v[180:183], v[220:223], a[48:63]
	ds_read_b128 v[180:183], v49 offset:9248
	ds_read_b128 v[184:187], v45 offset:64
	ds_read_b128 v[188:191], v45 offset:4672
	v_lshl_add_u64 v[50:51], v[0:1], 0, s[2:3]
	global_load_dwordx4 v[84:87], v[50:51], off
	v_lshl_add_u64 v[50:51], v[2:3], 0, s[2:3]
	s_or_b32 s2, s34, 0x50000
	global_load_dwordx4 v[88:91], v[50:51], off
	s_waitcnt lgkmcnt(7)
	v_mfma_f32_32x32x16_bf16 a[64:79], v[204:207], v[208:211], a[64:79]
	v_mfma_f32_32x32x16_bf16 a[80:95], v[204:207], v[212:215], a[80:95]
	v_mfma_f32_32x32x16_bf16 a[96:111], v[204:207], v[216:219], a[96:111]
	v_mfma_f32_32x32x16_bf16 a[112:127], v[204:207], v[220:223], a[112:127]
	ds_read_b128 v[204:207], v49 offset:13856
	ds_read_b128 v[192:195], v45 offset:9280
	ds_read_b128 v[196:199], v45 offset:13888
	v_lshl_add_u64 v[50:51], v[0:1], 0, s[2:3]
	global_load_dwordx4 v[92:95], v[50:51], off
	v_lshl_add_u64 v[50:51], v[2:3], 0, s[2:3]
	s_or_b32 s2, s34, 0x60000
	global_load_dwordx4 v[112:115], v[50:51], off
	s_waitcnt lgkmcnt(5)
	v_mfma_f32_32x32x16_bf16 a[128:143], v[180:183], v[208:211], a[128:143]
	v_mfma_f32_32x32x16_bf16 a[144:159], v[180:183], v[212:215], a[144:159]
	v_mfma_f32_32x32x16_bf16 a[160:175], v[180:183], v[216:219], a[160:175]
	v_mfma_f32_32x32x16_bf16 a[176:191], v[180:183], v[220:223], a[176:191]
	ds_read_b128 v[180:183], v49 offset:64
	v_lshl_add_u64 v[50:51], v[0:1], 0, s[2:3]
	global_load_dwordx4 v[124:127], v[50:51], off
	v_lshl_add_u64 v[50:51], v[2:3], 0, s[2:3]
	s_or_b32 s34, s34, 0x70000
	global_load_dwordx4 v[140:143], v[50:51], off
	s_waitcnt lgkmcnt(3)
	v_mfma_f32_32x32x16_bf16 a[192:207], v[204:207], v[208:211], a[192:207]
	v_mfma_f32_32x32x16_bf16 a[208:223], v[204:207], v[212:215], a[208:223]
	v_mfma_f32_32x32x16_bf16 a[224:239], v[204:207], v[216:219], a[224:239]
	v_mfma_f32_32x32x16_bf16 a[240:255], v[204:207], v[220:223], a[240:255]
	ds_read_b128 v[204:207], v49 offset:4672
	v_lshl_add_u64 v[50:51], v[0:1], 0, s[34:35]
	global_load_dwordx4 v[152:155], v[50:51], off
	v_lshl_add_u64 v[50:51], v[2:3], 0, s[34:35]
	global_load_dwordx4 v[172:175], v[50:51], off
	s_waitcnt vmcnt(27)
	ds_write_b128 v37, v[116:119]
	s_waitcnt vmcnt(26)
	ds_write_b128 v38, v[120:123]
	s_waitcnt vmcnt(25)
	ds_write_b128 v39, v[128:131]
	s_waitcnt vmcnt(24)
	ds_write_b128 v40, v[132:135]
	s_waitcnt lgkmcnt(5)
	v_mfma_f32_32x32x16_bf16 a[0:15], v[180:183], v[184:187], a[0:15]
	v_mfma_f32_32x32x16_bf16 a[16:31], v[180:183], v[188:191], a[16:31]
	v_mfma_f32_32x32x16_bf16 a[32:47], v[180:183], v[192:195], a[32:47]
	v_mfma_f32_32x32x16_bf16 a[48:63], v[180:183], v[196:199], a[48:63]
	ds_read_b128 v[180:183], v49 offset:9280
	ds_read_b128 v[208:211], v45 offset:96
	ds_read_b128 v[212:215], v45 offset:4704
	s_waitcnt lgkmcnt(7)
; #define GLOAD(RA, RB, kt) { _Pragma("unroll") for (int i = 0; i < 8; ++i) { const int ia = (tail && i >= 4) ? i - 4 : i; \
;     RA[i] = *(const u32x4*)(abase + ((size_t)(32 * ia) * lda + (kt) * 64) * 2 + aoff); RB[i] = *(const u32x4*)(bbase + ((size_t)(32 * i) * K + (kt) * 64) * 2 + boff); } }
; #define LWRITE(RA, RB, buf) { char* as_ = lds + (buf) * 2 * G_TILE; char* bs_ = as_ + G_TILE; _Pragma("unroll") for (int i = 0; i < 8; ++i) { *(u32x4*)(as_ + (lrow + 32 * i) * GS_B + lch * 16) = RA[i]; *(u32x4*)(bs_ + (lrow + 32 * i) * GS_B + lch * 16) = RB[i]; } }
; template <int EPI>
; DEV void gemm_tile(CParams& p, int layer, const bf16_t* __restrict__ A, int lda, const bf16_t* __restrict__ Bt, int K, int m0, int n0, int nt, char* lds, const int swave) {
;     ...
;   const char* asr = lds + (wm * 128 + lr) * GS_B + hh * 16;
;   const char* bsr = lds + G_TILE + (wn * 128 + lr) * GS_B + hh * 16;
;   char* wsw = lds + lrow * GS_B + lch * 16;
;     ...
;   GLOAD(ra0, rb0, 0); GLOAD(ra1, rb1, 1); LWRITE(ra0, rb0, 0); __syncthreads();
; #pragma unroll 1
;   for (int kt = 0; kt < nk; kt += 2) {
;     if (kt + 2 < nk) GLOAD(ra0, rb0, kt + 2);
;     COMPUTE(0, ra1, rb1, 1, true);
;     __syncthreads();
	v_mfma_f32_32x32x16_bf16 a[64:79], v[204:207], v[184:187], a[64:79]
	v_mfma_f32_32x32x16_bf16 a[80:95], v[204:207], v[188:191], a[80:95]
	v_mfma_f32_32x32x16_bf16 a[96:111], v[204:207], v[192:195], a[96:111]
	v_mfma_f32_32x32x16_bf16 a[112:127], v[204:207], v[196:199], a[112:127]
	ds_read_b128 v[204:207], v49 offset:13888
	ds_read_b128 v[216:219], v45 offset:9312
	ds_read_b128 v[220:223], v45 offset:13920
	s_waitcnt lgkmcnt(5)
	v_mfma_f32_32x32x16_bf16 a[128:143], v[180:183], v[184:187], a[128:143]
	v_mfma_f32_32x32x16_bf16 a[144:159], v[180:183], v[188:191], a[144:159]
	v_mfma_f32_32x32x16_bf16 a[160:175], v[180:183], v[192:195], a[160:175]
	v_mfma_f32_32x32x16_bf16 a[176:191], v[180:183], v[196:199], a[176:191]
	ds_read_b128 v[180:183], v49 offset:96
	s_waitcnt lgkmcnt(3)
	v_mfma_f32_32x32x16_bf16 a[192:207], v[204:207], v[184:187], a[192:207]
	v_mfma_f32_32x32x16_bf16 a[208:223], v[204:207], v[188:191], a[208:223]
	v_mfma_f32_32x32x16_bf16 a[224:239], v[204:207], v[192:195], a[224:239]
	v_mfma_f32_32x32x16_bf16 a[240:255], v[204:207], v[196:199], a[240:255]
	ds_read_b128 v[204:207], v49 offset:4704
	s_waitcnt vmcnt(23)
	ds_write_b128 v33, v[136:139]
	s_waitcnt vmcnt(22)
	ds_write_b128 v34, v[144:147]
	s_waitcnt vmcnt(21)
	ds_write_b128 v35, v[148:151]
	s_waitcnt vmcnt(20)
	ds_write_b128 v36, v[156:159]
	s_waitcnt lgkmcnt(5)
	v_mfma_f32_32x32x16_bf16 a[0:15], v[180:183], v[208:211], a[0:15]
	v_mfma_f32_32x32x16_bf16 a[16:31], v[180:183], v[212:215], a[16:31]
	v_mfma_f32_32x32x16_bf16 a[32:47], v[180:183], v[216:219], a[32:47]
	v_mfma_f32_32x32x16_bf16 a[48:63], v[180:183], v[220:223], a[48:63]
	ds_read_b128 v[180:183], v49 offset:9312
	s_waitcnt lgkmcnt(5)
	v_mfma_f32_32x32x16_bf16 a[64:79], v[204:207], v[208:211], a[64:79]
	v_mfma_f32_32x32x16_bf16 a[80:95], v[204:207], v[212:215], a[80:95]
	v_mfma_f32_32x32x16_bf16 a[96:111], v[204:207], v[216:219], a[96:111]
	v_mfma_f32_32x32x16_bf16 a[112:127], v[204:207], v[220:223], a[112:127]
	ds_read_b128 v[204:207], v49 offset:13920
	s_waitcnt lgkmcnt(1)
	v_mfma_f32_32x32x16_bf16 a[128:143], v[180:183], v[208:211], a[128:143]
	v_mfma_f32_32x32x16_bf16 a[144:159], v[180:183], v[212:215], a[144:159]
	v_mfma_f32_32x32x16_bf16 a[160:175], v[180:183], v[216:219], a[160:175]
	v_mfma_f32_32x32x16_bf16 a[176:191], v[180:183], v[220:223], a[176:191]
	s_waitcnt lgkmcnt(0)
	v_mfma_f32_32x32x16_bf16 a[192:207], v[204:207], v[208:211], a[192:207]
	v_mfma_f32_32x32x16_bf16 a[208:223], v[204:207], v[212:215], a[208:223]
	v_mfma_f32_32x32x16_bf16 a[224:239], v[204:207], v[216:219], a[224:239]
	v_mfma_f32_32x32x16_bf16 a[240:255], v[204:207], v[220:223], a[240:255]
	s_waitcnt vmcnt(19)
	ds_write_b128 v43, v[160:163]
	s_waitcnt vmcnt(18)
	ds_write_b128 v44, v[164:167]
	s_waitcnt vmcnt(17)
	ds_write_b128 v46, v[168:171]
	s_waitcnt vmcnt(16)
	ds_write_b128 v47, v[176:179]
	s_branch .LBB0_937
.Lzi_i3:
	ds_read_b128 v[184:187], v45
	ds_read_b128 v[188:191], v45 offset:4608
	ds_read_b128 v[192:195], v45 offset:9216
	ds_read_b128 v[196:199], v45 offset:13824
	ds_read_b128 v[180:183], v49
	ds_read_b128 v[204:207], v49 offset:4608
	s_waitcnt lgkmcnt(1)
	v_mfma_f32_32x32x16_bf16 a[0:15], v[180:183], v[184:187], a[0:15]
	v_mfma_f32_32x32x16_bf16 a[16:31], v[180:183], v[188:191], a[16:31]
	v_mfma_f32_32x32x16_bf16 a[32:47], v[180:183], v[192:195], a[32:47]
	v_mfma_f32_32x32x16_bf16 a[48:63], v[180:183], v[196:199], a[48:63]
	ds_read_b128 v[180:183], v49 offset:9216
	ds_read_b128 v[208:211], v45 offset:32
	ds_read_b128 v[212:215], v45 offset:4640
	v_lshl_add_u64 v[50:51], v[0:1], 0, s[34:35]
	global_load_dwordx4 v[52:55], v[50:51], off
	v_lshl_add_u64 v[50:51], v[2:3], 0, s[34:35]
	s_or_b32 s2, s34, 0x10000
	s_mov_b32 s3, s35
	global_load_dwordx4 v[56:59], v[50:51], off
	s_waitcnt lgkmcnt(3)
	v_mfma_f32_32x32x16_bf16 a[64:79], v[204:207], v[184:187], a[64:79]
	v_mfma_f32_32x32x16_bf16 a[80:95], v[204:207], v[188:191], a[80:95]
	v_mfma_f32_32x32x16_bf16 a[96:111], v[204:207], v[192:195], a[96:111]
	v_mfma_f32_32x32x16_bf16 a[112:127], v[204:207], v[196:199], a[112:127]
	ds_read_b128 v[204:207], v49 offset:13824
	ds_read_b128 v[216:219], v45 offset:9248
	ds_read_b128 v[220:223], v45 offset:13856
	v_lshl_add_u64 v[50:51], v[0:1], 0, s[2:3]
	global_load_dwordx4 v[60:63], v[50:51], off
	v_lshl_add_u64 v[50:51], v[2:3], 0, s[2:3]
	s_or_b32 s2, s34, 0x20000
	global_load_dwordx4 v[64:67], v[50:51], off
	s_waitcnt lgkmcnt(5)
	v_mfma_f32_32x32x16_bf16 a[128:143], v[180:183], v[184:187], a[128:143]
	v_mfma_f32_32x32x16_bf16 a[144:159], v[180:183], v[188:191], a[144:159]
	v_mfma_f32_32x32x16_bf16 a[160:175], v[180:183], v[192:195], a[160:175]
	v_mfma_f32_32x32x16_bf16 a[176:191], v[180:183], v[196:199], a[176:191]
	ds_read_b128 v[180:183], v49 offset:32
	v_lshl_add_u64 v[50:51], v[0:1], 0, s[2:3]
	global_load_dwordx4 v[68:71], v[50:51], off
	v_lshl_add_u64 v[50:51], v[2:3], 0, s[2:3]
	s_or_b32 s2, s34, 0x30000
	global_load_dwordx4 v[72:75], v[50:51], off
	s_waitcnt lgkmcnt(3)
	v_mfma_f32_32x32x16_bf16 a[192:207], v[204:207], v[184:187], a[192:207]
	v_mfma_f32_32x32x16_bf16 a[208:223], v[204:207], v[188:191], a[208:223]
	v_mfma_f32_32x32x16_bf16 a[224:239], v[204:207], v[192:195], a[224:239]
	v_mfma_f32_32x32x16_bf16 a[240:255], v[204:207], v[196:199], a[240:255]
	ds_read_b128 v[204:207], v49 offset:4640
	v_lshl_add_u64 v[50:51], v[0:1], 0, s[2:3]
	global_load_dwordx4 v[76:79], v[50:51], off
	v_lshl_add_u64 v[50:51], v[2:3], 0, s[2:3]
	s_or_b32 s2, s34, 0x40000
	global_load_dwordx4 v[80:83], v[50:51], off
	s_waitcnt vmcnt(23)
	ds_write_b128 v31, v[104:107]
	s_waitcnt vmcnt(22)
	ds_write_b128 v32, v[108:111]
	s_waitcnt vmcnt(21)
; #define GLOAD(RA, RB, kt) { _Pragma("unroll") for (int i = 0; i < 8; ++i) { const int ia = (tail && i >= 4) ? i - 4 : i; \
;     RA[i] = *(const u32x4*)(abase + ((size_t)(32 * ia) * lda + (kt) * 64) * 2 + aoff); RB[i] = *(const u32x4*)(bbase + ((size_t)(32 * i) * K + (kt) * 64) * 2 + boff); } }
; #define LWRITE(RA, RB, buf) { char* as_ = lds + (buf) * 2 * G_TILE; char* bs_ = as_ + G_TILE; _Pragma("unroll") for (int i = 0; i < 8; ++i) { *(u32x4*)(as_ + (lrow + 32 * i) * GS_B + lch * 16) = RA[i]; *(u32x4*)(bs_ + (lrow + 32 * i) * GS_B + lch * 16) = RB[i]; } }
; template <int EPI>
; DEV void gemm_tile(CParams& p, int layer, const bf16_t* __restrict__ A, int lda, const bf16_t* __restrict__ Bt, int K, int m0, int n0, int nt, char* lds, const int swave) {
;     ...
;   GLOAD(ra0, rb0, 0); GLOAD(ra1, rb1, 1); LWRITE(ra0, rb0, 0); __syncthreads();
; #pragma unroll 1
;   for (int kt = 0; kt < nk; kt += 2) {
;     if (kt + 2 < nk) GLOAD(ra0, rb0, kt + 2);
;     COMPUTE(0, ra1, rb1, 1, true);
;     __syncthreads();
	ds_write_b128 v41, v[96:99]
	s_waitcnt vmcnt(20)
	ds_write_b128 v42, v[100:103]
	s_waitcnt lgkmcnt(5)
	v_mfma_f32_32x32x16_bf16 a[0:15], v[180:183], v[208:211], a[0:15]
	v_mfma_f32_32x32x16_bf16 a[16:31], v[180:183], v[212:215], a[16:31]
	v_mfma_f32_32x32x16_bf16 a[32:47], v[180:183], v[216:219], a[32:47]
	v_mfma_f32_32x32x16_bf16 a[48:63], v[180:183], v[220:223], a[48:63]
	ds_read_b128 v[180:183], v49 offset:9248
	ds_read_b128 v[184:187], v45 offset:64
	ds_read_b128 v[188:191], v45 offset:4672
	v_lshl_add_u64 v[50:51], v[0:1], 0, s[2:3]
	global_load_dwordx4 v[84:87], v[50:51], off
	v_lshl_add_u64 v[50:51], v[2:3], 0, s[2:3]
	s_or_b32 s2, s34, 0x50000
	global_load_dwordx4 v[88:91], v[50:51], off
	s_waitcnt lgkmcnt(7)
	v_mfma_f32_32x32x16_bf16 a[64:79], v[204:207], v[208:211], a[64:79]
	v_mfma_f32_32x32x16_bf16 a[80:95], v[204:207], v[212:215], a[80:95]
	v_mfma_f32_32x32x16_bf16 a[96:111], v[204:207], v[216:219], a[96:111]
	v_mfma_f32_32x32x16_bf16 a[112:127], v[204:207], v[220:223], a[112:127]
	ds_read_b128 v[204:207], v49 offset:13856
	ds_read_b128 v[192:195], v45 offset:9280
	ds_read_b128 v[196:199], v45 offset:13888
	v_lshl_add_u64 v[50:51], v[0:1], 0, s[2:3]
	global_load_dwordx4 v[92:95], v[50:51], off
	v_lshl_add_u64 v[50:51], v[2:3], 0, s[2:3]
	s_or_b32 s2, s34, 0x60000
	global_load_dwordx4 v[112:115], v[50:51], off
	s_waitcnt lgkmcnt(5)
	v_mfma_f32_32x32x16_bf16 a[128:143], v[180:183], v[208:211], a[128:143]
	v_mfma_f32_32x32x16_bf16 a[144:159], v[180:183], v[212:215], a[144:159]
	v_mfma_f32_32x32x16_bf16 a[160:175], v[180:183], v[216:219], a[160:175]
	v_mfma_f32_32x32x16_bf16 a[176:191], v[180:183], v[220:223], a[176:191]
	ds_read_b128 v[180:183], v49 offset:64
	v_lshl_add_u64 v[50:51], v[0:1], 0, s[2:3]
	global_load_dwordx4 v[124:127], v[50:51], off
	v_lshl_add_u64 v[50:51], v[2:3], 0, s[2:3]
	s_or_b32 s34, s34, 0x70000
	global_load_dwordx4 v[140:143], v[50:51], off
	s_waitcnt lgkmcnt(3)
	v_mfma_f32_32x32x16_bf16 a[192:207], v[204:207], v[208:211], a[192:207]
	v_mfma_f32_32x32x16_bf16 a[208:223], v[204:207], v[212:215], a[208:223]
	v_mfma_f32_32x32x16_bf16 a[224:239], v[204:207], v[216:219], a[224:239]
	v_mfma_f32_32x32x16_bf16 a[240:255], v[204:207], v[220:223], a[240:255]
	ds_read_b128 v[204:207], v49 offset:4672
	v_lshl_add_u64 v[50:51], v[0:1], 0, s[34:35]
	global_load_dwordx4 v[152:155], v[50:51], off
	v_lshl_add_u64 v[50:51], v[2:3], 0, s[34:35]
	global_load_dwordx4 v[172:175], v[50:51], off
	s_waitcnt vmcnt(27)
	ds_write_b128 v37, v[116:119]
	s_waitcnt vmcnt(26)
	ds_write_b128 v38, v[120:123]
	s_waitcnt vmcnt(25)
	ds_write_b128 v39, v[128:131]
	s_waitcnt vmcnt(24)
	ds_write_b128 v40, v[132:135]
	s_waitcnt lgkmcnt(5)
	v_mfma_f32_32x32x16_bf16 a[0:15], v[180:183], v[184:187], a[0:15]
	v_mfma_f32_32x32x16_bf16 a[16:31], v[180:183], v[188:191], a[16:31]
	v_mfma_f32_32x32x16_bf16 a[32:47], v[180:183], v[192:195], a[32:47]
	v_mfma_f32_32x32x16_bf16 a[48:63], v[180:183], v[196:199], a[48:63]
	ds_read_b128 v[180:183], v49 offset:9280
	ds_read_b128 v[208:211], v45 offset:96
	ds_read_b128 v[212:215], v45 offset:4704
	s_waitcnt lgkmcnt(7)
	v_mfma_f32_32x32x16_bf16 a[64:79], v[204:207], v[184:187], a[64:79]
	v_mfma_f32_32x32x16_bf16 a[80:95], v[204:207], v[188:191], a[80:95]
	v_mfma_f32_32x32x16_bf16 a[96:111], v[204:207], v[192:195], a[96:111]
	v_mfma_f32_32x32x16_bf16 a[112:127], v[204:207], v[196:199], a[112:127]
	ds_read_b128 v[204:207], v49 offset:13888
	ds_read_b128 v[216:219], v45 offset:9312
	ds_read_b128 v[220:223], v45 offset:13920
	s_waitcnt lgkmcnt(5)
	v_mfma_f32_32x32x16_bf16 a[128:143], v[180:183], v[184:187], a[128:143]
	v_mfma_f32_32x32x16_bf16 a[144:159], v[180:183], v[188:191], a[144:159]
	v_mfma_f32_32x32x16_bf16 a[160:175], v[180:183], v[192:195], a[160:175]
	v_mfma_f32_32x32x16_bf16 a[176:191], v[180:183], v[196:199], a[176:191]
	ds_read_b128 v[180:183], v49 offset:96
	s_waitcnt lgkmcnt(3)
	v_mfma_f32_32x32x16_bf16 a[192:207], v[204:207], v[184:187], a[192:207]
	v_mfma_f32_32x32x16_bf16 a[208:223], v[204:207], v[188:191], a[208:223]
	v_mfma_f32_32x32x16_bf16 a[224:239], v[204:207], v[192:195], a[224:239]
	v_mfma_f32_32x32x16_bf16 a[240:255], v[204:207], v[196:199], a[240:255]
	ds_read_b128 v[204:207], v49 offset:4704
	s_waitcnt vmcnt(23)
	ds_write_b128 v33, v[136:139]
	s_waitcnt vmcnt(22)
	ds_write_b128 v34, v[144:147]
	s_waitcnt vmcnt(21)
	ds_write_b128 v35, v[148:151]
	s_waitcnt vmcnt(20)
	ds_write_b128 v36, v[156:159]
	s_waitcnt lgkmcnt(5)
	v_mfma_f32_32x32x16_bf16 a[0:15], v[180:183], v[208:211], a[0:15]
	v_mfma_f32_32x32x16_bf16 a[16:31], v[180:183], v[212:215], a[16:31]
	v_mfma_f32_32x32x16_bf16 a[32:47], v[180:183], v[216:219], a[32:47]
	v_mfma_f32_32x32x16_bf16 a[48:63], v[180:183], v[220:223], a[48:63]
	ds_read_b128 v[180:183], v49 offset:9312
	s_waitcnt lgkmcnt(5)
	v_mfma_f32_32x32x16_bf16 a[64:79], v[204:207], v[208:211], a[64:79]
	v_mfma_f32_32x32x16_bf16 a[80:95], v[204:207], v[212:215], a[80:95]
	v_mfma_f32_32x32x16_bf16 a[96:111], v[204:207], v[216:219], a[96:111]
	v_mfma_f32_32x32x16_bf16 a[112:127], v[204:207], v[220:223], a[112:127]
	ds_read_b128 v[204:207], v49 offset:13920
	s_waitcnt lgkmcnt(1)
	v_mfma_f32_32x32x16_bf16 a[128:143], v[180:183], v[208:211], a[128:143]
	v_mfma_f32_32x32x16_bf16 a[144:159], v[180:183], v[212:215], a[144:159]
	v_mfma_f32_32x32x16_bf16 a[160:175], v[180:183], v[216:219], a[160:175]
	v_mfma_f32_32x32x16_bf16 a[176:191], v[180:183], v[220:223], a[176:191]
	s_waitcnt lgkmcnt(0)
	v_mfma_f32_32x32x16_bf16 a[192:207], v[204:207], v[208:211], a[192:207]
	v_mfma_f32_32x32x16_bf16 a[208:223], v[204:207], v[212:215], a[208:223]
	v_mfma_f32_32x32x16_bf16 a[224:239], v[204:207], v[216:219], a[224:239]
	v_mfma_f32_32x32x16_bf16 a[240:255], v[204:207], v[220:223], a[240:255]
	s_waitcnt vmcnt(19)
	ds_write_b128 v43, v[160:163]
	s_waitcnt vmcnt(18)
	ds_write_b128 v44, v[164:167]
	s_waitcnt vmcnt(17)
	ds_write_b128 v46, v[168:171]
	s_waitcnt vmcnt(16)
	ds_write_b128 v47, v[176:179]

; #define GLOAD(RA, RB, kt) { _Pragma("unroll") for (int i = 0; i < 8; ++i) { const int ia = (tail && i >= 4) ? i - 4 : i; \
;     RA[i] = *(const u32x4*)(abase + ((size_t)(32 * ia) * lda + (kt) * 64) * 2 + aoff); RB[i] = *(const u32x4*)(bbase + ((size_t)(32 * i) * K + (kt) * 64) * 2 + boff); } }
; #define LWRITE(RA, RB, buf) { char* as_ = lds + (buf) * 2 * G_TILE; char* bs_ = as_ + G_TILE; _Pragma("unroll") for (int i = 0; i < 8; ++i) { *(u32x4*)(as_ + (lrow + 32 * i) * GS_B + lch * 16) = RA[i]; *(u32x4*)(bs_ + (lrow + 32 * i) * GS_B + lch * 16) = RB[i]; } }
; template <int EPI>
; DEV void gemm_tile(CParams& p, int layer, const bf16_t* __restrict__ A, int lda, const bf16_t* __restrict__ Bt, int K, int m0, int n0, int nt, char* lds, const int swave) {
;     ...
;   const char* asr = lds + (wm * 128 + lr) * GS_B + hh * 16;
;   const char* bsr = lds + G_TILE + (wn * 128 + lr) * GS_B + hh * 16;
;   char* wsw = lds + lrow * GS_B + lch * 16;
;     ...
;   GLOAD(ra0, rb0, 0); GLOAD(ra1, rb1, 1); LWRITE(ra0, rb0, 0); __syncthreads();
; #pragma unroll 1
;   for (int kt = 0; kt < nk; kt += 2) {
;     if (kt + 2 < nk) GLOAD(ra0, rb0, kt + 2);
;     COMPUTE(0, ra1, rb1, 1, true);
;     __syncthreads();
;     const bool more = kt + 2 < nk;
;     if (kt + 3 < nk) GLOAD(ra1, rb1, kt + 3);
;     COMPUTE(1, ra0, rb0, 0, more);
;     __syncthreads();
.LBB0_939:
	v_add_u32_e32 v224, 0x1b000, v29
	v_add_u32_e32 v225, 0x12000, v45
	s_andn2_b64 vcc, exec, s[60:61]
	s_cbranch_vccnz .Lpg_i3_nomore
	ds_read_b128 v[184:187], v225
	ds_read_b128 v[188:191], v225 offset:4608
	ds_read_b128 v[192:195], v225 offset:9216
	ds_read_b128 v[196:199], v225 offset:13824
	ds_read_b128 v[180:183], v224
	ds_read_b128 v[204:207], v224 offset:4608
	s_waitcnt lgkmcnt(1)
	v_mfma_f32_32x32x16_bf16 a[0:15], v[180:183], v[184:187], a[0:15]
	v_mfma_f32_32x32x16_bf16 a[16:31], v[180:183], v[188:191], a[16:31]
	v_mfma_f32_32x32x16_bf16 a[32:47], v[180:183], v[192:195], a[32:47]
	v_mfma_f32_32x32x16_bf16 a[48:63], v[180:183], v[196:199], a[48:63]
	ds_read_b128 v[180:183], v224 offset:9216
	ds_read_b128 v[208:211], v225 offset:32
	ds_read_b128 v[212:215], v225 offset:4640
	s_lshl_b32 s34, s42, 7
	v_lshl_add_u64 v[50:51], v[0:1], 0, s[34:35]
	v_lshl_add_u64 v[96:97], v[2:3], 0, s[34:35]
	global_load_dwordx4 v[104:107], v[50:51], off offset:384
	global_load_dwordx4 v[108:111], v[96:97], off offset:384
	s_waitcnt lgkmcnt(3)
	v_mfma_f32_32x32x16_bf16 a[64:79], v[204:207], v[184:187], a[64:79]
	v_mfma_f32_32x32x16_bf16 a[80:95], v[204:207], v[188:191], a[80:95]
	v_mfma_f32_32x32x16_bf16 a[96:111], v[204:207], v[192:195], a[96:111]
	v_mfma_f32_32x32x16_bf16 a[112:127], v[204:207], v[196:199], a[112:127]
	ds_read_b128 v[204:207], v224 offset:13824
	ds_read_b128 v[216:219], v225 offset:9248
	ds_read_b128 v[220:223], v225 offset:13856
	v_add_co_u32_e32 v50, vcc, 0x10000, v50
	v_lshl_add_u64 v[120:121], v[6:7], 0, s[34:35]
	v_addc_co_u32_e32 v51, vcc, 0, v51, vcc
	v_add_co_u32_e32 v100, vcc, 0x10000, v96
	v_lshl_add_u64 v[132:133], v[10:11], 0, s[34:35]
	v_addc_co_u32_e32 v101, vcc, 0, v97, vcc
	global_load_dwordx4 v[96:99], v[50:51], off offset:384
	s_nop 0
	global_load_dwordx4 v[100:103], v[100:101], off offset:384
	s_waitcnt lgkmcnt(5)
	v_mfma_f32_32x32x16_bf16 a[128:143], v[180:183], v[184:187], a[128:143]
	v_mfma_f32_32x32x16_bf16 a[144:159], v[180:183], v[188:191], a[144:159]
	v_mfma_f32_32x32x16_bf16 a[160:175], v[180:183], v[192:195], a[160:175]
	v_mfma_f32_32x32x16_bf16 a[176:191], v[180:183], v[196:199], a[176:191]
	ds_read_b128 v[180:183], v224 offset:32
	v_lshl_add_u64 v[50:51], v[4:5], 0, s[34:35]
	global_load_dwordx4 v[116:119], v[50:51], off offset:384
	s_nop 0
	global_load_dwordx4 v[120:123], v[120:121], off offset:384
	s_waitcnt lgkmcnt(3)
	v_mfma_f32_32x32x16_bf16 a[192:207], v[204:207], v[184:187], a[192:207]
	v_mfma_f32_32x32x16_bf16 a[208:223], v[204:207], v[188:191], a[208:223]
	v_mfma_f32_32x32x16_bf16 a[224:239], v[204:207], v[192:195], a[224:239]
	v_mfma_f32_32x32x16_bf16 a[240:255], v[204:207], v[196:199], a[240:255]
	ds_read_b128 v[204:207], v224 offset:4640
	v_lshl_add_u64 v[50:51], v[8:9], 0, s[34:35]
	global_load_dwordx4 v[128:131], v[50:51], off offset:384
	s_nop 0
	global_load_dwordx4 v[132:135], v[132:133], off offset:384
	s_waitcnt vmcnt(23)
	ds_write_b128 v30, v[52:55]
	s_waitcnt vmcnt(22)
	ds_write_b128 v30, v[56:59] offset:36864
	s_waitcnt vmcnt(21)
	ds_write_b128 v30, v[60:63] offset:4608
	s_waitcnt vmcnt(20)
	ds_write_b128 v30, v[64:67] offset:41472
	s_waitcnt lgkmcnt(5)
	v_mfma_f32_32x32x16_bf16 a[0:15], v[180:183], v[208:211], a[0:15]
	v_mfma_f32_32x32x16_bf16 a[16:31], v[180:183], v[212:215], a[16:31]
	v_mfma_f32_32x32x16_bf16 a[32:47], v[180:183], v[216:219], a[32:47]
	v_mfma_f32_32x32x16_bf16 a[48:63], v[180:183], v[220:223], a[48:63]
	ds_read_b128 v[180:183], v224 offset:9248
	ds_read_b128 v[184:187], v225 offset:64
	ds_read_b128 v[188:191], v225 offset:4672
	v_lshl_add_u64 v[50:51], v[12:13], 0, s[34:35]
	v_lshl_add_u64 v[144:145], v[14:15], 0, s[34:35]
	global_load_dwordx4 v[136:139], v[50:51], off offset:384
	s_nop 0
	global_load_dwordx4 v[144:147], v[144:145], off offset:384
	s_waitcnt lgkmcnt(7)
	v_mfma_f32_32x32x16_bf16 a[64:79], v[204:207], v[208:211], a[64:79]
	v_mfma_f32_32x32x16_bf16 a[80:95], v[204:207], v[212:215], a[80:95]
	v_mfma_f32_32x32x16_bf16 a[96:111], v[204:207], v[216:219], a[96:111]
	v_mfma_f32_32x32x16_bf16 a[112:127], v[204:207], v[220:223], a[112:127]
	ds_read_b128 v[204:207], v224 offset:13856
	ds_read_b128 v[192:195], v225 offset:9280
	ds_read_b128 v[196:199], v225 offset:13888
	v_lshl_add_u64 v[50:51], v[16:17], 0, s[34:35]
	v_lshl_add_u64 v[156:157], v[18:19], 0, s[34:35]
	global_load_dwordx4 v[148:151], v[50:51], off offset:384
	s_nop 0
	global_load_dwordx4 v[156:159], v[156:157], off offset:384
	s_waitcnt lgkmcnt(5)
; #define GLOAD(RA, RB, kt) { _Pragma("unroll") for (int i = 0; i < 8; ++i) { const int ia = (tail && i >= 4) ? i - 4 : i; \
;     RA[i] = *(const u32x4*)(abase + ((size_t)(32 * ia) * lda + (kt) * 64) * 2 + aoff); RB[i] = *(const u32x4*)(bbase + ((size_t)(32 * i) * K + (kt) * 64) * 2 + boff); } }
; #define LWRITE(RA, RB, buf) { char* as_ = lds + (buf) * 2 * G_TILE; char* bs_ = as_ + G_TILE; _Pragma("unroll") for (int i = 0; i < 8; ++i) { *(u32x4*)(as_ + (lrow + 32 * i) * GS_B + lch * 16) = RA[i]; *(u32x4*)(bs_ + (lrow + 32 * i) * GS_B + lch * 16) = RB[i]; } }
; template <int EPI>
; DEV void gemm_tile(CParams& p, int layer, const bf16_t* __restrict__ A, int lda, const bf16_t* __restrict__ Bt, int K, int m0, int n0, int nt, char* lds, const int swave) {
;     ...
;   GLOAD(ra0, rb0, 0); GLOAD(ra1, rb1, 1); LWRITE(ra0, rb0, 0); __syncthreads();
; #pragma unroll 1
;   for (int kt = 0; kt < nk; kt += 2) {
;     if (kt + 2 < nk) GLOAD(ra0, rb0, kt + 2);
;     COMPUTE(0, ra1, rb1, 1, true);
;     __syncthreads();
;     const bool more = kt + 2 < nk;
;     if (kt + 3 < nk) GLOAD(ra1, rb1, kt + 3);
;     COMPUTE(1, ra0, rb0, 0, more);
;     __syncthreads();
;   }
	v_mfma_f32_32x32x16_bf16 a[128:143], v[180:183], v[208:211], a[128:143]
	v_mfma_f32_32x32x16_bf16 a[144:159], v[180:183], v[212:215], a[144:159]
	v_mfma_f32_32x32x16_bf16 a[160:175], v[180:183], v[216:219], a[160:175]
	v_mfma_f32_32x32x16_bf16 a[176:191], v[180:183], v[220:223], a[176:191]
	ds_read_b128 v[180:183], v224 offset:64
	v_lshl_add_u64 v[50:51], v[20:21], 0, s[34:35]
	v_lshl_add_u64 v[164:165], v[22:23], 0, s[34:35]
	global_load_dwordx4 v[160:163], v[50:51], off offset:384
	s_nop 0
	global_load_dwordx4 v[164:167], v[164:165], off offset:384
	s_waitcnt lgkmcnt(3)
	v_mfma_f32_32x32x16_bf16 a[192:207], v[204:207], v[208:211], a[192:207]
	v_mfma_f32_32x32x16_bf16 a[208:223], v[204:207], v[212:215], a[208:223]
	v_mfma_f32_32x32x16_bf16 a[224:239], v[204:207], v[216:219], a[224:239]
	v_mfma_f32_32x32x16_bf16 a[240:255], v[204:207], v[220:223], a[240:255]
	ds_read_b128 v[204:207], v224 offset:4672
	v_lshl_add_u64 v[50:51], v[24:25], 0, s[34:35]
	v_lshl_add_u64 v[176:177], v[26:27], 0, s[34:35]
	global_load_dwordx4 v[168:171], v[50:51], off offset:384
	s_nop 0
	global_load_dwordx4 v[176:179], v[176:177], off offset:384
	s_waitcnt vmcnt(27)
	ds_write_b128 v30, v[68:71] offset:9216
	s_waitcnt vmcnt(26)
	ds_write_b128 v30, v[72:75] offset:46080
	s_waitcnt vmcnt(25)
	ds_write_b128 v30, v[76:79] offset:13824
	s_waitcnt vmcnt(24)
	ds_write_b128 v30, v[80:83] offset:50688
	s_waitcnt lgkmcnt(5)
	v_mfma_f32_32x32x16_bf16 a[0:15], v[180:183], v[184:187], a[0:15]
	v_mfma_f32_32x32x16_bf16 a[16:31], v[180:183], v[188:191], a[16:31]
	v_mfma_f32_32x32x16_bf16 a[32:47], v[180:183], v[192:195], a[32:47]
	v_mfma_f32_32x32x16_bf16 a[48:63], v[180:183], v[196:199], a[48:63]
	ds_read_b128 v[180:183], v224 offset:9280
	ds_read_b128 v[208:211], v225 offset:96
	ds_read_b128 v[212:215], v225 offset:4704
	s_waitcnt lgkmcnt(7)
	v_mfma_f32_32x32x16_bf16 a[64:79], v[204:207], v[184:187], a[64:79]
	v_mfma_f32_32x32x16_bf16 a[80:95], v[204:207], v[188:191], a[80:95]
	v_mfma_f32_32x32x16_bf16 a[96:111], v[204:207], v[192:195], a[96:111]
	v_mfma_f32_32x32x16_bf16 a[112:127], v[204:207], v[196:199], a[112:127]
	ds_read_b128 v[204:207], v224 offset:13888
	ds_read_b128 v[216:219], v225 offset:9312
	ds_read_b128 v[220:223], v225 offset:13920
	s_waitcnt lgkmcnt(5)
	v_mfma_f32_32x32x16_bf16 a[128:143], v[180:183], v[184:187], a[128:143]
	v_mfma_f32_32x32x16_bf16 a[144:159], v[180:183], v[188:191], a[144:159]
	v_mfma_f32_32x32x16_bf16 a[160:175], v[180:183], v[192:195], a[160:175]
	v_mfma_f32_32x32x16_bf16 a[176:191], v[180:183], v[196:199], a[176:191]
	ds_read_b128 v[180:183], v224 offset:96
	s_waitcnt lgkmcnt(3)
	v_mfma_f32_32x32x16_bf16 a[192:207], v[204:207], v[184:187], a[192:207]
	v_mfma_f32_32x32x16_bf16 a[208:223], v[204:207], v[188:191], a[208:223]
	v_mfma_f32_32x32x16_bf16 a[224:239], v[204:207], v[192:195], a[224:239]
	v_mfma_f32_32x32x16_bf16 a[240:255], v[204:207], v[196:199], a[240:255]
	ds_read_b128 v[204:207], v224 offset:4704
	s_waitcnt vmcnt(23)
	ds_write_b128 v30, v[84:87] offset:18432
	s_waitcnt vmcnt(22)
	ds_write_b128 v30, v[88:91] offset:55296
	s_waitcnt vmcnt(21)
	ds_write_b128 v30, v[92:95] offset:23040
	s_waitcnt vmcnt(20)
	ds_write_b128 v30, v[112:115] offset:59904
	s_waitcnt lgkmcnt(5)
	v_mfma_f32_32x32x16_bf16 a[0:15], v[180:183], v[208:211], a[0:15]
	v_mfma_f32_32x32x16_bf16 a[16:31], v[180:183], v[212:215], a[16:31]
	v_mfma_f32_32x32x16_bf16 a[32:47], v[180:183], v[216:219], a[32:47]
	v_mfma_f32_32x32x16_bf16 a[48:63], v[180:183], v[220:223], a[48:63]
	ds_read_b128 v[180:183], v224 offset:9312
	s_waitcnt lgkmcnt(5)
	v_mfma_f32_32x32x16_bf16 a[64:79], v[204:207], v[208:211], a[64:79]
	v_mfma_f32_32x32x16_bf16 a[80:95], v[204:207], v[212:215], a[80:95]
	v_mfma_f32_32x32x16_bf16 a[96:111], v[204:207], v[216:219], a[96:111]
	v_mfma_f32_32x32x16_bf16 a[112:127], v[204:207], v[220:223], a[112:127]
	ds_read_b128 v[204:207], v224 offset:13920
	s_waitcnt lgkmcnt(1)
	v_mfma_f32_32x32x16_bf16 a[128:143], v[180:183], v[208:211], a[128:143]
	v_mfma_f32_32x32x16_bf16 a[144:159], v[180:183], v[212:215], a[144:159]
	v_mfma_f32_32x32x16_bf16 a[160:175], v[180:183], v[216:219], a[160:175]
	v_mfma_f32_32x32x16_bf16 a[176:191], v[180:183], v[220:223], a[176:191]
	s_waitcnt lgkmcnt(0)
	v_mfma_f32_32x32x16_bf16 a[192:207], v[204:207], v[208:211], a[192:207]
	v_mfma_f32_32x32x16_bf16 a[208:223], v[204:207], v[212:215], a[208:223]
	v_mfma_f32_32x32x16_bf16 a[224:239], v[204:207], v[216:219], a[224:239]
	v_mfma_f32_32x32x16_bf16 a[240:255], v[204:207], v[220:223], a[240:255]
	s_waitcnt vmcnt(19)
	ds_write_b128 v30, v[124:127] offset:27648
	s_waitcnt vmcnt(18)
	ds_write_b128 v30, v[140:143] offset:64512
	s_waitcnt vmcnt(17)
	ds_write_b128 v30, v[152:155] offset:32256
	s_waitcnt vmcnt(16)
	ds_write_b128 v48, v[172:175]
	s_branch .LBB0_918
